# GEMM1: previous tile's 16 epilogue stores stay in flight across the next tile's K-loop start (tile prologue vmcnt(16), peeled first body with relaxed waits); flips deleted; side_gemm1 coalesced
# baseline (speedup 1.0000x reference)
; #define PG8_STAGE(bufoff, gbase, voff) do { _Pragma("unroll") for (int _i = 0; _i < 2; ++_i) \
;         __builtin_amdgcn_global_load_lds((const unsigned*)((const char*)(gbase) + (voff)[_i]), (PG8_LAS unsigned*)(lds + (bufoff) + ldsw + _i * 8192), 16, 0, 0); } while (0)
; #define PG8_WAIT_V(n) asm volatile("s_waitcnt vmcnt(" #n ")" ::: "memory")
; #define PG8_BAR __builtin_amdgcn_s_barrier()
; template <class Epi, class Sched, bool ALIGN_EPI = false, bool SP2 = false>
; __device__ __forceinline__ void gemm_phase(PG8_LAS unsigned char* lds, const Gemm g, const Sched& S, const Epi& E) {
;     int tid_l = threadIdx.x; asm volatile("" : "+v"(tid_l)); const int tid = tid_l, wid = __builtin_amdgcn_readfirstlane(tid >> 6), lane = tid & 63, wr = wid >> 2, wc = wid & 3, fr = lane & 15, fq = lane >> 4;
;     const int K = g.K, nt = K / BK;
;     unsigned voffA[2], voffB[2];
; #pragma unroll
;     for (int i = 0; i < 2; ++i) { int R, C; stage_rc(tid * 16 + i * 8192, R, C); const int Rb = Epi::PERM ? ((R & ~31) + perm32(R & 31)) : R;
;         voffA[i] = (unsigned)(R * K + C) * 2u; voffB[i] = (unsigned)(Rb * K + C) * 2u; }
;     const size_t kstep = (size_t)(BK * 2);
;     const size_t hstep = (size_t)HALF * K * 2;
;     const size_t tstep = 2 * hstep;
;     const unsigned ldsw = (unsigned)wid * 1024u;
;     const int aoff = lds_byte(wr * 64 + fr, fq * 8), boff = lds_byte(wc * 32 + fr, fq * 8);
;     ...
;     if constexpr (SP2) {
;         PG8_STAGE(PG8_SB(0, 0), cB, voffB); PG8_STAGE(PG8_SB(0, 1), cB + hstep, voffB); PG8_STAGE(PG8_SA(0, 0), cA, voffA); PG8_STAGE(PG8_SA(0, 1), cA + hstep, voffA);
;         if (wr == 1) PG8_BAR;
;         PG8_WAIT_V(2); PG8_BAR;
.LBB0_77:
	v_readlane_b32 s0, v254, 40
	v_readlane_b32 s1, v254, 41
	s_mov_b32 s9, s82
	v_writelane_b32 v254, s0, 40
	v_mov_b32_e32 v12, v172
	s_mov_b32 s84, 0x2aaaaaab
	v_writelane_b32 v254, s1, 41
	v_readlane_b32 s0, v252, 43
	v_readlane_b32 s1, v252, 44
	v_writelane_b32 v255, s48, 1
	s_andn2_b64 vcc, exec, s[0:1]
	v_readfirstlane_b32 s16, v12
	s_cbranch_vccnz .LBB0_93
	s_mov_b32 s101, 0
	v_lshlrev_b32_e32 v4, 4, v12
	s_waitcnt lgkmcnt(0)
	v_add_u32_e32 v5, 0x2000, v4
	v_ashrrev_i32_e32 v6, 31, v5
	v_lshrrev_b32_e32 v6, 22, v6
	v_add_u32_e32 v6, v5, v6
	v_ashrrev_i32_e32 v13, 10, v6
	v_mul_i32_i24_e32 v6, 0x400, v13
	v_sub_u32_e32 v5, v5, v6
	v_lshrrev_b32_e32 v6, 4, v5
	v_bitop3_b32 v5, v6, v5, 32 bitop3:0x6c
	v_ashrrev_i32_e32 v6, 31, v5
	v_lshrrev_b32_e32 v6, 26, v6
	v_add_u32_e32 v6, v5, v6
	v_lshlrev_b32_e32 v7, 3, v13
	v_ashrrev_i32_e32 v14, 6, v6
	v_and_b32_e32 v7, -16, v7
	v_add_u32_e32 v7, v14, v7
	v_and_b32_e32 v8, 3, v14
	s_mov_b32 s14, 0xfffe0
	v_lshrrev_b32_e32 v9, 2, v7
	v_lshlrev_b32_e32 v10, 1, v7
	v_and_b32_e32 v6, 0xc0, v6
	v_and_or_b32 v8, v7, s14, v8
	v_and_b32_e32 v9, 4, v9
	v_and_b32_e32 v10, 24, v10
	v_sub_u32_e32 v5, v5, v6
	v_or3_b32 v8, v8, v9, v10
	v_lshlrev_b32_e32 v9, 5, v13
	v_ashrrev_i16_sdwa v5, v238, sext(v5) dst_sel:DWORD dst_unused:UNUSED_PAD src0_sel:DWORD src1_sel:BYTE_0
	v_and_b32_e32 v9, 32, v9
	v_bfe_i32 v15, v5, 0, 16
	v_add_lshl_u32 v5, v9, v15, 1
	v_lshl_add_u32 v132, v8, 12, v5
	v_lshl_add_u32 v134, v7, 12, v5
	v_bfe_i32 v5, v12, 27, 1
	v_readlane_b32 s0, v254, 38
	v_lshrrev_b32_e32 v5, 22, v5
	v_readlane_b32 s1, v254, 39
	s_mul_i32 s20, s0, 0x2100
	v_add_u32_e32 v5, v4, v5
	s_lshl_b64 s[0:1], s[20:21], 12
	v_readlane_b32 s12, v254, 40
	v_and_b32_e32 v5, 0xfffffc00, v5
	v_readlane_b32 s13, v254, 41
	s_add_u32 s0, s12, s0
	v_sub_u32_e32 v4, v4, v5
	s_addc_u32 s1, s13, s1
	v_lshrrev_b32_e32 v5, 4, v4
	v_ashrrev_i32_e32 v6, 31, v12
	s_add_u32 s22, s0, 0xb0c0000
	v_bitop3_b32 v4, v5, v4, 32 bitop3:0x6c
	v_lshrrev_b32_e32 v6, 26, v6
	s_addc_u32 s23, s1, 0
	v_readlane_b32 s0, v252, 50
	v_ashrrev_i32_e32 v5, 31, v4
	v_add_u32_e32 v6, v12, v6
	v_readlane_b32 s1, v252, 51
	s_add_u32 s38, s12, s0
	v_lshrrev_b32_e32 v5, 26, v5
	v_ashrrev_i32_e32 v17, 6, v6
	s_addc_u32 s39, s13, s1
	v_readlane_b32 s0, v252, 48
	v_add_u32_e32 v5, v4, v5
	v_lshlrev_b32_e32 v6, 3, v17
	v_readlane_b32 s1, v252, 49
	s_add_u32 s40, s22, s0
	v_ashrrev_i32_e32 v16, 6, v5
	v_and_b32_e32 v6, -16, v6
	s_addc_u32 s41, s23, s1
	s_ashr_i32 s17, s16, 6
	v_add_u32_e32 v6, v16, v6
	s_ashr_i32 s18, s16, 8
	s_lshl_b32 s24, s17, 10
	v_and_b32_e32 v7, 3, v16
	v_lshrrev_b32_e32 v8, 2, v6
	v_lshlrev_b32_e32 v9, 1, v6
	v_and_b32_e32 v5, 0xc0, v5
	s_add_u32 s0, s40, 0x80000
	v_and_or_b32 v7, v6, s14, v7
	v_and_b32_e32 v8, 4, v8
	v_and_b32_e32 v9, 24, v9
	v_sub_u32_e32 v4, v4, v5
	s_addc_u32 s1, s41, 0
	v_or3_b32 v7, v7, v8, v9
	v_lshlrev_b32_e32 v8, 5, v17
	v_ashrrev_i16_sdwa v4, v238, sext(v4) dst_sel:DWORD dst_unused:UNUSED_PAD src0_sel:DWORD src1_sel:BYTE_0
	s_add_u32 s12, s38, 0x80000
	v_and_b32_e32 v8, 32, v8
	v_bfe_i32 v18, v4, 0, 16
	s_addc_u32 s13, s39, 0
	v_add_lshl_u32 v4, v8, v18, 1
	s_add_i32 s25, s24, 0
	v_lshl_add_u32 v174, v7, 12, v4
	s_add_i32 m0, s25, 0x10000
	v_lshl_add_u32 v136, v6, 12, v4
	global_load_lds_dwordx4 v174, s[38:39]
	s_add_i32 m0, s25, 0x12000
	s_add_i32 s42, s25, 0x2000
	global_load_lds_dwordx4 v132, s[38:39]
	s_add_i32 m0, s25, 0x14000
	s_add_i32 s43, s25, 0x4000
	global_load_lds_dwordx4 v174, s[12:13]
	s_add_i32 m0, s25, 0x16000
	s_add_i32 s44, s25, 0x6000
	global_load_lds_dwordx4 v132, s[12:13]
	s_mov_b32 m0, s25
	v_mov_b32_e32 v133, v175
	global_load_lds_dwordx4 v136, s[40:41]
	s_mov_b32 m0, s42
	v_mov_b32_e32 v137, v175
	global_load_lds_dwordx4 v134, s[40:41]
	s_mov_b32 m0, s43
	v_mov_b32_e32 v135, v175
	global_load_lds_dwordx4 v136, s[0:1]
	s_mov_b32 m0, s44
	s_cmp_eq_u32 s18, 1
	global_load_lds_dwordx4 v134, s[0:1]
	v_lshl_add_u64 v[10:11], s[38:39], 0, v[174:175]
	v_lshl_add_u64 v[8:9], s[38:39], 0, v[132:133]
	v_lshl_add_u64 v[4:5], s[40:41], 0, v[136:137]
	s_cselect_b64 s[0:1], -1, 0
	s_cmp_lg_u32 s18, 1
	v_lshl_add_u64 v[6:7], s[40:41], 0, v[134:135]
	s_cbranch_scc1 .LBB0_80
	s_barrier

; template <class Epi, class Sched, bool ALIGN_EPI = false, bool SP2 = false>
; __device__ __forceinline__ void gemm_phase(PG8_LAS unsigned char* lds, const Gemm g, const Sched& S, const Epi& E) {
;     ...
;         const bool has_next = S.next(ui + 1, nxt);
;         const char* nA = has_next ? (const char*)g.A + (size_t)nxt.pm * tstep : cA; const char* nB = has_next ? (const char*)g.Bt + (size_t)nxt.pn * tstep : cB;
;     ...
; #pragma unroll
;         for (int a = 0; a < 2; ++a)
; #pragma unroll
;             for (int b = 0; b < 2; ++b)
; #pragma unroll
;                 for (int m = 0; m < 4; ++m)
; #pragma unroll
;                     for (int n = 0; n < 2; ++n) acc[a][b][m][n] = (f32x4){0.f, 0.f, 0.f, 0.f};
;         cur = nxt; cA = nA; cB = nB; ++ui;
.LBB0_85:
	s_ashr_i32 s29, s28, 31
	s_lshl_b64 s[26:27], s[28:29], 20
	s_add_u32 s30, s22, s26
	s_addc_u32 s31, s23, s27
	s_and_b64 s[26:27], s[36:37], exec
	s_cselect_b32 s29, s31, s41
	s_cselect_b32 s50, s30, s40
	s_ashr_i32 s19, s18, 31
	s_lshl_b64 s[26:27], s[18:19], 20
	v_readlane_b32 s34, v254, 40
	v_readlane_b32 s35, v254, 41
	s_add_u32 s34, s34, s26
	s_addc_u32 s35, s35, s27
	s_and_b64 s[26:27], s[36:37], exec
	s_cselect_b32 s19, s35, s39
	s_cselect_b32 s51, s34, s38
	s_add_u32 s52, s38, 0x100
	s_addc_u32 s53, s39, 0
	s_add_u32 s38, s40, 0x80080
	v_mov_b32_e32 v4, 0
	s_addc_u32 s39, s41, 0
	s_mov_b32 s54, -2
	v_mov_b32_e32 v5, v4
	v_mov_b32_e32 v6, v4
	v_mov_b32_e32 v7, v4
	v_mov_b32_e32 v8, v4
	v_mov_b32_e32 v9, v4
	v_mov_b32_e32 v10, v4
	v_mov_b32_e32 v11, v4
	v_mov_b32_e32 v16, v4
	v_mov_b32_e32 v17, v4
	v_mov_b32_e32 v18, v4
	v_mov_b32_e32 v19, v4
	v_mov_b32_e32 v24, v4
	v_mov_b32_e32 v25, v4
	v_mov_b32_e32 v26, v4
	v_mov_b32_e32 v27, v4
	s_cmp_lg_u32 s101, 0
	s_cbranch_scc1 .Lg1_w16
	s_waitcnt vmcnt(0)
	s_branch .Lg1_wdone
.Lg1_w16:
	s_waitcnt vmcnt(16)
.Lg1_wdone:
	v_mov_b32_e32 v32, v4
	v_mov_b32_e32 v33, v4
	v_mov_b32_e32 v34, v4
	v_mov_b32_e32 v35, v4
	v_mov_b32_e32 v40, v4
	v_mov_b32_e32 v41, v4
	v_mov_b32_e32 v42, v4
	v_mov_b32_e32 v43, v4
	v_mov_b32_e32 v48, v4
	v_mov_b32_e32 v49, v4
	v_mov_b32_e32 v50, v4
	v_mov_b32_e32 v51, v4
	v_mov_b32_e32 v56, v4
	v_mov_b32_e32 v57, v4
	v_mov_b32_e32 v58, v4
	v_mov_b32_e32 v59, v4
	v_mov_b32_e32 v12, v4
	v_mov_b32_e32 v13, v4
	v_mov_b32_e32 v14, v4
	v_mov_b32_e32 v15, v4
	v_mov_b32_e32 v20, v4
	v_mov_b32_e32 v21, v4
	v_mov_b32_e32 v22, v4
	v_mov_b32_e32 v23, v4
	v_mov_b32_e32 v28, v4
	v_mov_b32_e32 v29, v4
	v_mov_b32_e32 v30, v4
	v_mov_b32_e32 v31, v4
	v_mov_b32_e32 v36, v4
	v_mov_b32_e32 v37, v4
	v_mov_b32_e32 v38, v4
	v_mov_b32_e32 v39, v4
	v_mov_b32_e32 v44, v4
	v_mov_b32_e32 v45, v4
	v_mov_b32_e32 v46, v4
	v_mov_b32_e32 v47, v4
	v_mov_b32_e32 v52, v4
	v_mov_b32_e32 v53, v4
	v_mov_b32_e32 v54, v4
	v_mov_b32_e32 v55, v4
	v_mov_b32_e32 v60, v4
	v_mov_b32_e32 v61, v4
	v_mov_b32_e32 v62, v4
	v_mov_b32_e32 v63, v4
	v_mov_b32_e32 v64, v4
	v_mov_b32_e32 v65, v4
	v_mov_b32_e32 v66, v4
	v_mov_b32_e32 v67, v4
	v_mov_b32_e32 v68, v4
	v_mov_b32_e32 v69, v4
	v_mov_b32_e32 v70, v4
	v_mov_b32_e32 v71, v4
	v_mov_b32_e32 v72, v4
	v_mov_b32_e32 v73, v4
	v_mov_b32_e32 v74, v4
	v_mov_b32_e32 v75, v4
	v_mov_b32_e32 v84, v4
	v_mov_b32_e32 v85, v4
	v_mov_b32_e32 v86, v4
	v_mov_b32_e32 v87, v4
	v_mov_b32_e32 v88, v4
	v_mov_b32_e32 v89, v4
	v_mov_b32_e32 v90, v4
	v_mov_b32_e32 v91, v4
	v_mov_b32_e32 v100, v4
	v_mov_b32_e32 v101, v4
	v_mov_b32_e32 v102, v4
	v_mov_b32_e32 v103, v4
	v_mov_b32_e32 v104, v4
	v_mov_b32_e32 v105, v4
	v_mov_b32_e32 v106, v4
	v_mov_b32_e32 v107, v4
	v_mov_b32_e32 v116, v4
	v_mov_b32_e32 v117, v4
	v_mov_b32_e32 v118, v4
	v_mov_b32_e32 v119, v4
	v_mov_b32_e32 v120, v4
	v_mov_b32_e32 v121, v4
	v_mov_b32_e32 v122, v4
	v_mov_b32_e32 v123, v4
	v_mov_b32_e32 v76, v4
	v_mov_b32_e32 v77, v4
	v_mov_b32_e32 v78, v4
	v_mov_b32_e32 v79, v4
	v_mov_b32_e32 v80, v4
	v_mov_b32_e32 v81, v4
	v_mov_b32_e32 v82, v4
	v_mov_b32_e32 v83, v4
	v_mov_b32_e32 v92, v4
	v_mov_b32_e32 v93, v4
	v_mov_b32_e32 v94, v4
	v_mov_b32_e32 v95, v4
	v_mov_b32_e32 v96, v4
	v_mov_b32_e32 v97, v4
	v_mov_b32_e32 v98, v4
	v_mov_b32_e32 v99, v4
	v_mov_b32_e32 v108, v4
	v_mov_b32_e32 v109, v4
	v_mov_b32_e32 v110, v4
	v_mov_b32_e32 v111, v4
	v_mov_b32_e32 v112, v4
	v_mov_b32_e32 v113, v4
	v_mov_b32_e32 v114, v4
	v_mov_b32_e32 v115, v4
	v_mov_b32_e32 v124, v4
	v_mov_b32_e32 v125, v4
	v_mov_b32_e32 v126, v4
	v_mov_b32_e32 v127, v4
	v_mov_b32_e32 v128, v4
	v_mov_b32_e32 v129, v4
	v_mov_b32_e32 v130, v4
	v_mov_b32_e32 v131, v4
	s_setprio 0
	s_cmp_lg_u32 s101, 0
	s_cbranch_scc1 .Lg1_peel

; __device__ __forceinline__ unsigned cvt_pk_bf16(float lo, float hi) { unsigned r; asm volatile("v_cvt_pk_bf16_f32 %0, %1, %2" : "=v"(r) : "v"(lo), "v"(hi)); return r; }
; #define GAS __attribute__((address_space(1)))
;     __device__ __forceinline__ void operator()(const f32x4 (&acc)[2][2][4][2], const pg8::Unit& u, int wr, int wc, int fr, int fq) const {
;         const int row0 = u.pm * 256 + wr * 64 + fr, col0 = u.pn * 256 + wc * 32 + 8 * fq;
;         float rs[8];
; #pragma unroll
;         for (int i = 0; i < 8; ++i) rs[i] = rstd[row0 + (i >> 2) * 128 + (i & 3) * 16];
; #pragma unroll
;         for (int ai = 0; ai < 2; ++ai)
; #pragma unroll
;             for (int m = 0; m < 4; ++m) { const int row = row0 + ai * 128 + m * 16; const float r = rs[ai * 4 + m]; GAS bf16* rowp = O + (size_t)row * NPROJ + col0;
; #pragma unroll
;                 for (int bj = 0; bj < 2; ++bj) { const f32x4 v0 = acc[ai][bj][m][0] * r, v1 = acc[ai][bj][m][1] * r; v4u w;
;                     w.x = cvt_pk_bf16(v0[0], v0[1]); w.y = cvt_pk_bf16(v0[2], v0[3]); w.z = cvt_pk_bf16(v1[0], v1[1]); w.w = cvt_pk_bf16(v1[2], v1[3]);
;                     *(GAS v4u*)(rowp + bj * 128) = w; } }
.LBB0_89:
	v_lshl_add_u32 v144, s49, 8, v143
	v_ashrrev_i32_e32 v145, 31, v144
	v_lshl_add_u64 v[148:149], v[144:145], 2, s[14:15]
	global_load_dword v160, v[148:149], off
	global_load_dword v162, v[148:149], off offset:64
	global_load_dword v158, v[148:149], off offset:128
	global_load_dword v156, v[148:149], off offset:192
	global_load_dword v154, v[148:149], off offset:512
	global_load_dword v152, v[148:149], off offset:576
	global_load_dword v146, v[148:149], off offset:640
	global_load_dword v142, v[148:149], off offset:704
	v_lshl_or_b32 v150, s48, 8, v153
	v_ashrrev_i32_e32 v151, 31, v150
	v_mov_b64_e32 v[148:149], s[12:13]
	v_mad_i64_i32 v[164:165], s[26:27], v144, s4, v[148:149]
	v_lshlrev_b64 v[150:151], 1, v[150:151]
	v_lshl_add_u64 v[164:165], v[164:165], 0, v[150:151]
	v_add_u32_e32 v145, 0x80, v144
	s_andn2_b64 vcc, exec, s[36:37]
	s_waitcnt vmcnt(0)
	v_pk_mul_f32 v[130:131], v[130:131], v[160:161] op_sel_hi:[1,0]
	v_pk_mul_f32 v[128:129], v[128:129], v[160:161] op_sel_hi:[1,0]
	v_pk_mul_f32 v[166:167], v[126:127], v[160:161] op_sel_hi:[1,0]
	v_pk_mul_f32 v[126:127], v[124:125], v[160:161] op_sel_hi:[1,0]
	v_cvt_pk_bf16_f32 v124, v128, v129
	v_cvt_pk_bf16_f32 v125, v130, v131
	v_pk_mul_f32 v[120:121], v[120:121], v[160:161] op_sel_hi:[1,0]
	v_cvt_pk_bf16_f32 v126, v126, v127
	v_cvt_pk_bf16_f32 v127, v166, v167
	global_store_dwordx4 v[164:165], v[124:127], off
	v_pk_mul_f32 v[122:123], v[122:123], v[160:161] op_sel_hi:[1,0]
	v_pk_mul_f32 v[114:115], v[114:115], v[162:163] op_sel_hi:[1,0]
	v_pk_mul_f32 v[124:125], v[118:119], v[160:161] op_sel_hi:[1,0]
	v_pk_mul_f32 v[118:119], v[116:117], v[160:161] op_sel_hi:[1,0]
	v_cvt_pk_bf16_f32 v116, v120, v121
	v_cvt_pk_bf16_f32 v117, v122, v123
	v_pk_mul_f32 v[112:113], v[112:113], v[162:163] op_sel_hi:[1,0]
	v_cvt_pk_bf16_f32 v118, v118, v119
	v_cvt_pk_bf16_f32 v119, v124, v125
	global_store_dwordx4 v[164:165], v[116:119], off offset:256
	v_pk_mul_f32 v[104:105], v[104:105], v[162:163] op_sel_hi:[1,0]
	v_pk_mul_f32 v[106:107], v[106:107], v[162:163] op_sel_hi:[1,0]
	v_or_b32_e32 v116, 16, v144
	v_mad_i64_i32 v[116:117], s[26:27], v116, s4, v[148:149]
	v_lshl_add_u64 v[116:117], v[116:117], 0, v[150:151]
	v_pk_mul_f32 v[118:119], v[110:111], v[162:163] op_sel_hi:[1,0]
	v_pk_mul_f32 v[110:111], v[108:109], v[162:163] op_sel_hi:[1,0]
	v_cvt_pk_bf16_f32 v108, v112, v113
	v_cvt_pk_bf16_f32 v109, v114, v115
	v_pk_mul_f32 v[98:99], v[98:99], v[158:159] op_sel_hi:[1,0]
	v_cvt_pk_bf16_f32 v110, v110, v111
	v_cvt_pk_bf16_f32 v111, v118, v119
	global_store_dwordx4 v[116:117], v[108:111], off
	v_pk_mul_f32 v[96:97], v[96:97], v[158:159] op_sel_hi:[1,0]
	v_pk_mul_f32 v[88:89], v[88:89], v[158:159] op_sel_hi:[1,0]
	v_pk_mul_f32 v[108:109], v[102:103], v[162:163] op_sel_hi:[1,0]
	v_pk_mul_f32 v[102:103], v[100:101], v[162:163] op_sel_hi:[1,0]
	v_cvt_pk_bf16_f32 v100, v104, v105
	v_cvt_pk_bf16_f32 v101, v106, v107
	v_pk_mul_f32 v[90:91], v[90:91], v[158:159] op_sel_hi:[1,0]
	v_cvt_pk_bf16_f32 v102, v102, v103
	v_cvt_pk_bf16_f32 v103, v108, v109
	global_store_dwordx4 v[116:117], v[100:103], off offset:256
	v_pk_mul_f32 v[82:83], v[82:83], v[156:157] op_sel_hi:[1,0]
	v_pk_mul_f32 v[80:81], v[80:81], v[156:157] op_sel_hi:[1,0]
	v_or_b32_e32 v100, 32, v144
	v_mad_i64_i32 v[100:101], s[26:27], v100, s4, v[148:149]
	v_lshl_add_u64 v[100:101], v[100:101], 0, v[150:151]
	v_pk_mul_f32 v[102:103], v[94:95], v[158:159] op_sel_hi:[1,0]
	v_pk_mul_f32 v[94:95], v[92:93], v[158:159] op_sel_hi:[1,0]
	v_cvt_pk_bf16_f32 v92, v96, v97
	v_cvt_pk_bf16_f32 v93, v98, v99
	v_pk_mul_f32 v[74:75], v[74:75], v[156:157] op_sel_hi:[1,0]
	v_cvt_pk_bf16_f32 v94, v94, v95
	v_cvt_pk_bf16_f32 v95, v102, v103
	global_store_dwordx4 v[100:101], v[92:95], off
	v_pk_mul_f32 v[72:73], v[72:73], v[156:157] op_sel_hi:[1,0]
	v_pk_mul_f32 v[66:67], v[66:67], v[154:155] op_sel_hi:[1,0]
	v_pk_mul_f32 v[92:93], v[86:87], v[158:159] op_sel_hi:[1,0]
	v_pk_mul_f32 v[86:87], v[84:85], v[158:159] op_sel_hi:[1,0]
	v_cvt_pk_bf16_f32 v84, v88, v89
	v_cvt_pk_bf16_f32 v85, v90, v91
	v_pk_mul_f32 v[64:65], v[64:65], v[154:155] op_sel_hi:[1,0]
	v_cvt_pk_bf16_f32 v86, v86, v87
	v_cvt_pk_bf16_f32 v87, v92, v93
	global_store_dwordx4 v[100:101], v[84:87], off offset:256
	v_pk_mul_f32 v[56:57], v[56:57], v[154:155] op_sel_hi:[1,0]
	v_pk_mul_f32 v[58:59], v[58:59], v[154:155] op_sel_hi:[1,0]
	v_or_b32_e32 v84, 48, v144
	v_mad_i64_i32 v[84:85], s[26:27], v84, s4, v[148:149]
	v_lshl_add_u64 v[84:85], v[84:85], 0, v[150:151]
	v_pk_mul_f32 v[86:87], v[78:79], v[156:157] op_sel_hi:[1,0]
	v_pk_mul_f32 v[78:79], v[76:77], v[156:157] op_sel_hi:[1,0]
	v_cvt_pk_bf16_f32 v76, v80, v81
	v_cvt_pk_bf16_f32 v77, v82, v83
	v_pk_mul_f32 v[52:53], v[52:53], v[152:153] op_sel_hi:[1,0]
	v_cvt_pk_bf16_f32 v78, v78, v79
	v_cvt_pk_bf16_f32 v79, v86, v87
	global_store_dwordx4 v[84:85], v[76:79], off
	v_pk_mul_f32 v[40:41], v[40:41], v[152:153] op_sel_hi:[1,0]
	v_pk_mul_f32 v[42:43], v[42:43], v[152:153] op_sel_hi:[1,0]
	v_pk_mul_f32 v[76:77], v[70:71], v[156:157] op_sel_hi:[1,0]
	v_pk_mul_f32 v[70:71], v[68:69], v[156:157] op_sel_hi:[1,0]
	v_cvt_pk_bf16_f32 v68, v72, v73
	v_cvt_pk_bf16_f32 v69, v74, v75
	v_pk_mul_f32 v[36:37], v[36:37], v[146:147] op_sel_hi:[1,0]
	v_cvt_pk_bf16_f32 v70, v70, v71
	v_cvt_pk_bf16_f32 v71, v76, v77
	global_store_dwordx4 v[84:85], v[68:71], off offset:256
	v_pk_mul_f32 v[24:25], v[24:25], v[146:147] op_sel_hi:[1,0]
	v_pk_mul_f32 v[26:27], v[26:27], v[146:147] op_sel_hi:[1,0]
	v_mad_i64_i32 v[68:69], s[26:27], v145, s4, v[148:149]
	v_lshl_add_u64 v[68:69], v[68:69], 0, v[150:151]
	v_pk_mul_f32 v[70:71], v[62:63], v[154:155] op_sel_hi:[1,0]
; __device__ __forceinline__ unsigned cvt_pk_bf16(float lo, float hi) { unsigned r; asm volatile("v_cvt_pk_bf16_f32 %0, %1, %2" : "=v"(r) : "v"(lo), "v"(hi)); return r; }
; #define PG8_STAGE(bufoff, gbase, voff) do { _Pragma("unroll") for (int _i = 0; _i < 2; ++_i) \
;         __builtin_amdgcn_global_load_lds((const unsigned*)((const char*)(gbase) + (voff)[_i]), (PG8_LAS unsigned*)(lds + (bufoff) + ldsw + _i * 8192), 16, 0, 0); } while (0)
; #define PG8_LDA(dst, b, h) do { _Pragma("unroll") for (int m = 0; m < 4; ++m) _Pragma("unroll") for (int k = 0; k < 2; ++k) dst[m][k] = *(const PG8_LAS bf16x8*)(lds + PG8_SA(b, h) + aoff + m * 2048 + k * 1024); } while (0)
; #define PG8_LDB(dst, b, h) do { _Pragma("unroll") for (int n = 0; n < 2; ++n) _Pragma("unroll") for (int k = 0; k < 2; ++k) dst[n][k] = *(const PG8_LAS bf16x8*)(lds + PG8_SB(b, h) + boff + n * 2048 + k * 1024); } while (0)
; #define PG8_MMA(ai, bj, At, Bt) do { __builtin_amdgcn_s_setprio(1); _Pragma("unroll") for (int m = 0; m < 4; ++m) _Pragma("unroll") for (int n = 0; n < 2; ++n) _Pragma("unroll") for (int k = 0; k < 2; ++k) \
;         acc[ai][bj][m][n] = __builtin_amdgcn_mfma_f32_16x16x32_bf16(Bt[n][k], At[m][k], acc[ai][bj][m][n], 0, 0, 0); __builtin_amdgcn_s_setprio(0); } while (0)
; template <class Epi, class Sched, bool ALIGN_EPI = false, bool SP2 = false>
; __device__ __forceinline__ void gemm_phase(PG8_LAS unsigned char* lds, const Gemm g, const Sched& S, const Epi& E) {
;     ...
;             PG8_LDB(B0, 0, 0); PG8_LDB(B1, 0, 1); PG8_SCHED; PG8_LDA(At, 0, 0); PG8_STAGE(PG8_SA(1, 1), a1 + hstep, voffA);
;             PG8_WAIT_V(8); PG8_WAIT_L(0); PG8_BAR; PG8_MMA(0, 0, At, B0); PG8_MMA(0, 1, At, B1); PG8_BAR; PG8_SCHED;
;     __device__ __forceinline__ void operator()(const f32x4 (&acc)[2][2][4][2], const pg8::Unit& u, int wr, int wc, int fr, int fq) const {
;     ...
;             for (int m = 0; m < 4; ++m) { const int row = row0 + ai * 128 + m * 16; const float r = rs[ai * 4 + m]; GAS bf16* rowp = O + (size_t)row * NPROJ + col0;
; #pragma unroll
;                 for (int bj = 0; bj < 2; ++bj) { const f32x4 v0 = acc[ai][bj][m][0] * r, v1 = acc[ai][bj][m][1] * r; v4u w;
;                     w.x = cvt_pk_bf16(v0[0], v0[1]); w.y = cvt_pk_bf16(v0[2], v0[3]); w.z = cvt_pk_bf16(v1[0], v1[1]); w.w = cvt_pk_bf16(v1[2], v1[3]);
;                     *(GAS v4u*)(rowp + bj * 128) = w; } }
	v_pk_mul_f32 v[62:63], v[60:61], v[154:155] op_sel_hi:[1,0]
	v_cvt_pk_bf16_f32 v60, v64, v65
	v_cvt_pk_bf16_f32 v61, v66, v67
	v_pk_mul_f32 v[20:21], v[20:21], v[142:143] op_sel_hi:[1,0]
	v_cvt_pk_bf16_f32 v62, v62, v63
	v_cvt_pk_bf16_f32 v63, v70, v71
	global_store_dwordx4 v[68:69], v[60:63], off
	v_pk_mul_f32 v[10:11], v[10:11], v[142:143] op_sel_hi:[1,0]
	v_pk_mul_f32 v[8:9], v[8:9], v[142:143] op_sel_hi:[1,0]
	v_pk_mul_f32 v[60:61], v[50:51], v[154:155] op_sel_hi:[1,0]
	v_pk_mul_f32 v[50:51], v[48:49], v[154:155] op_sel_hi:[1,0]
	v_cvt_pk_bf16_f32 v48, v56, v57
	v_cvt_pk_bf16_f32 v49, v58, v59
	s_nop 0
	v_cvt_pk_bf16_f32 v50, v50, v51
	v_cvt_pk_bf16_f32 v51, v60, v61
	global_store_dwordx4 v[68:69], v[48:51], off offset:256
	s_nop 1
	v_add_u32_e32 v48, 0x90, v144
	v_mad_i64_i32 v[48:49], s[26:27], v48, s4, v[148:149]
	v_lshl_add_u64 v[48:49], v[48:49], 0, v[150:151]
	v_pk_mul_f32 v[50:51], v[54:55], v[152:153] op_sel_hi:[1,0]
	v_pk_mul_f32 v[54:55], v[46:47], v[152:153] op_sel_hi:[1,0]
	v_pk_mul_f32 v[46:47], v[44:45], v[152:153] op_sel_hi:[1,0]
	v_cvt_pk_bf16_f32 v44, v52, v53
	v_cvt_pk_bf16_f32 v45, v50, v51
	s_nop 0
	v_cvt_pk_bf16_f32 v46, v46, v47
	v_cvt_pk_bf16_f32 v47, v54, v55
	global_store_dwordx4 v[48:49], v[44:47], off
	s_nop 1
	v_pk_mul_f32 v[44:45], v[34:35], v[152:153] op_sel_hi:[1,0]
	v_pk_mul_f32 v[34:35], v[32:33], v[152:153] op_sel_hi:[1,0]
	v_cvt_pk_bf16_f32 v32, v40, v41
	v_cvt_pk_bf16_f32 v33, v42, v43
	s_nop 0
	v_cvt_pk_bf16_f32 v34, v34, v35
	v_cvt_pk_bf16_f32 v35, v44, v45
	global_store_dwordx4 v[48:49], v[32:35], off offset:256
	s_nop 1
	v_add_u32_e32 v32, 0xa0, v144
	v_mad_i64_i32 v[32:33], s[26:27], v32, s4, v[148:149]
	v_lshl_add_u64 v[32:33], v[32:33], 0, v[150:151]
	v_pk_mul_f32 v[34:35], v[38:39], v[146:147] op_sel_hi:[1,0]
	v_pk_mul_f32 v[38:39], v[30:31], v[146:147] op_sel_hi:[1,0]
	v_pk_mul_f32 v[30:31], v[28:29], v[146:147] op_sel_hi:[1,0]
	v_cvt_pk_bf16_f32 v28, v36, v37
	v_cvt_pk_bf16_f32 v29, v34, v35
	s_nop 0
	v_cvt_pk_bf16_f32 v30, v30, v31
	v_cvt_pk_bf16_f32 v31, v38, v39
	global_store_dwordx4 v[32:33], v[28:31], off
	s_nop 1
	v_pk_mul_f32 v[28:29], v[18:19], v[146:147] op_sel_hi:[1,0]
	v_pk_mul_f32 v[18:19], v[16:17], v[146:147] op_sel_hi:[1,0]
	v_cvt_pk_bf16_f32 v16, v24, v25
	v_cvt_pk_bf16_f32 v17, v26, v27
	s_nop 0
	v_cvt_pk_bf16_f32 v18, v18, v19
	v_cvt_pk_bf16_f32 v19, v28, v29
	global_store_dwordx4 v[32:33], v[16:19], off offset:256
	s_nop 1
	v_add_u32_e32 v16, 0xb0, v144
	v_mad_i64_i32 v[16:17], s[26:27], v16, s4, v[148:149]
	v_lshl_add_u64 v[16:17], v[16:17], 0, v[150:151]
	v_pk_mul_f32 v[18:19], v[22:23], v[142:143] op_sel_hi:[1,0]
	v_pk_mul_f32 v[22:23], v[14:15], v[142:143] op_sel_hi:[1,0]
	v_pk_mul_f32 v[14:15], v[12:13], v[142:143] op_sel_hi:[1,0]
	v_cvt_pk_bf16_f32 v12, v20, v21
	v_cvt_pk_bf16_f32 v13, v18, v19
	s_mov_b64 s[26:27], -1
	v_cvt_pk_bf16_f32 v14, v14, v15
	v_cvt_pk_bf16_f32 v15, v22, v23
	global_store_dwordx4 v[16:17], v[12:15], off
	s_nop 1
	v_pk_mul_f32 v[12:13], v[6:7], v[142:143] op_sel_hi:[1,0]
	v_pk_mul_f32 v[6:7], v[4:5], v[142:143] op_sel_hi:[1,0]
	v_cvt_pk_bf16_f32 v4, v8, v9
	v_cvt_pk_bf16_f32 v5, v10, v11
	s_nop 0
	v_cvt_pk_bf16_f32 v6, v6, v7
	v_cvt_pk_bf16_f32 v7, v12, v13
	global_store_dwordx4 v[16:17], v[4:7], off offset:256
	s_mov_b32 s101, 1
	s_cbranch_vccnz .LBB0_82
	s_andn2_b64 vcc, exec, s[0:1]
	s_cbranch_vccnz .LBB0_81
	s_barrier
	s_branch .LBB0_81
.Lg1_peel:
	s_add_u32 s26, s38, 0xfff80080
	s_addc_u32 s27, s39, -1
	s_add_i32 s55, 0, 0x10000
	s_cmp_eq_u32 s54, 28
	s_cselect_b32 s27, s29, s27
	s_cselect_b32 s26, s50, s26
	v_add_u32_e32 v142, s55, v147
	s_cselect_b32 s41, s19, s53
	s_cselect_b32 s40, s51, s52
	s_add_i32 s58, 0, 0x14000
	ds_read_b128 v[148:151], v142
	ds_read_b128 v[156:159], v142 offset:1024
	ds_read_b128 v[160:163], v142 offset:2048
	ds_read_b128 v[164:167], v142 offset:3072
	v_add_u32_e32 v142, s58, v147
	ds_read_b128 v[168:171], v142
	ds_read_b128 v[184:187], v142 offset:1024
	ds_read_b128 v[188:191], v142 offset:2048
	ds_read_b128 v[192:195], v142 offset:3072
	v_lshl_add_u64 v[144:145], s[38:39], 0, v[140:141]
	s_add_i32 m0, s25, 0xc000
	ds_read_b128 v[196:199], v155
	ds_read_b128 v[200:203], v155 offset:1024
	ds_read_b128 v[204:207], v155 offset:2048
	ds_read_b128 v[208:211], v155 offset:3072
	ds_read_b128 v[212:215], v155 offset:4096
	ds_read_b128 v[216:219], v155 offset:5120
	ds_read_b128 v[220:223], v155 offset:6144
	ds_read_b128 v[224:227], v155 offset:7168
	global_load_lds_dwordx4 v[144:145], off
	v_lshl_add_u64 v[144:145], s[38:39], 0, v[138:139]
	s_add_i32 m0, s25, 0xe000
	s_nop 0
	global_load_lds_dwordx4 v[144:145], off
	s_waitcnt vmcnt(24)
	s_waitcnt lgkmcnt(0)
	s_barrier
; #define PG8_STAGE(bufoff, gbase, voff) do { _Pragma("unroll") for (int _i = 0; _i < 2; ++_i) \
;         __builtin_amdgcn_global_load_lds((const unsigned*)((const char*)(gbase) + (voff)[_i]), (PG8_LAS unsigned*)(lds + (bufoff) + ldsw + _i * 8192), 16, 0, 0); } while (0)
; #define PG8_LDA(dst, b, h) do { _Pragma("unroll") for (int m = 0; m < 4; ++m) _Pragma("unroll") for (int k = 0; k < 2; ++k) dst[m][k] = *(const PG8_LAS bf16x8*)(lds + PG8_SA(b, h) + aoff + m * 2048 + k * 1024); } while (0)
; #define PG8_MMA(ai, bj, At, Bt) do { __builtin_amdgcn_s_setprio(1); _Pragma("unroll") for (int m = 0; m < 4; ++m) _Pragma("unroll") for (int n = 0; n < 2; ++n) _Pragma("unroll") for (int k = 0; k < 2; ++k) \
;         acc[ai][bj][m][n] = __builtin_amdgcn_mfma_f32_16x16x32_bf16(Bt[n][k], At[m][k], acc[ai][bj][m][n], 0, 0, 0); __builtin_amdgcn_s_setprio(0); } while (0)
; #define PG8_WAIT_V(n) asm volatile("s_waitcnt vmcnt(" #n ")" ::: "memory")
; #define PG8_WAIT_L(n) asm volatile("s_waitcnt lgkmcnt(" #n ")" ::: "memory")
; #define PG8_BAR __builtin_amdgcn_s_barrier()
; #define PG8_SCHED __builtin_amdgcn_sched_barrier(0)
; template <class Epi, class Sched, bool ALIGN_EPI = false, bool SP2 = false>
; __device__ __forceinline__ void gemm_phase(PG8_LAS unsigned char* lds, const Gemm g, const Sched& S, const Epi& E) {
;     ...
;             PG8_WAIT_V(8); PG8_WAIT_L(0); PG8_BAR; PG8_MMA(0, 0, At, B0); PG8_MMA(0, 1, At, B1); PG8_BAR; PG8_SCHED;
;             PG8_LDA(At, 0, 1); PG8_STAGE(PG8_SB(0, 0), b2, voffB); PG8_STAGE(PG8_SB(0, 1), b2 + hstep, voffB); PG8_STAGE(PG8_SA(0, 0), a2, voffA);
;             PG8_WAIT_V(8); PG8_WAIT_L(0); PG8_BAR; PG8_MMA(1, 0, At, B0); PG8_MMA(1, 1, At, B1); PG8_BAR; PG8_SCHED;
	s_waitcnt lgkmcnt(0)
	v_mfma_f32_16x16x32_bf16 v[128:131], v[148:151], v[196:199], v[128:131]
	v_mfma_f32_16x16x32_bf16 v[124:127], v[160:163], v[196:199], v[124:127]
	v_mfma_f32_16x16x32_bf16 v[112:115], v[148:151], v[204:207], v[112:115]
	v_mfma_f32_16x16x32_bf16 v[108:111], v[160:163], v[204:207], v[108:111]
	v_mfma_f32_16x16x32_bf16 v[96:99], v[148:151], v[212:215], v[96:99]
	v_mfma_f32_16x16x32_bf16 v[92:95], v[160:163], v[212:215], v[92:95]
	v_mfma_f32_16x16x32_bf16 v[80:83], v[148:151], v[220:223], v[80:83]
	v_mfma_f32_16x16x32_bf16 v[76:79], v[160:163], v[220:223], v[76:79]
	v_mfma_f32_16x16x32_bf16 v[128:131], v[156:159], v[200:203], v[128:131]
	v_mfma_f32_16x16x32_bf16 v[124:127], v[164:167], v[200:203], v[124:127]
	v_mfma_f32_16x16x32_bf16 v[112:115], v[156:159], v[208:211], v[112:115]
	v_mfma_f32_16x16x32_bf16 v[108:111], v[164:167], v[208:211], v[108:111]
	v_mfma_f32_16x16x32_bf16 v[96:99], v[156:159], v[216:219], v[96:99]
	v_mfma_f32_16x16x32_bf16 v[92:95], v[164:167], v[216:219], v[92:95]
	v_mfma_f32_16x16x32_bf16 v[80:83], v[156:159], v[224:227], v[80:83]
	v_mfma_f32_16x16x32_bf16 v[76:79], v[164:167], v[224:227], v[76:79]
	v_mfma_f32_16x16x32_bf16 v[120:123], v[168:171], v[196:199], v[120:123]
	v_mfma_f32_16x16x32_bf16 v[116:119], v[188:191], v[196:199], v[116:119]
	v_mfma_f32_16x16x32_bf16 v[104:107], v[168:171], v[204:207], v[104:107]
	v_mfma_f32_16x16x32_bf16 v[100:103], v[188:191], v[204:207], v[100:103]
	v_mfma_f32_16x16x32_bf16 v[88:91], v[168:171], v[212:215], v[88:91]
	v_mfma_f32_16x16x32_bf16 v[84:87], v[188:191], v[212:215], v[84:87]
	v_mfma_f32_16x16x32_bf16 v[72:75], v[168:171], v[220:223], v[72:75]
	v_mfma_f32_16x16x32_bf16 v[68:71], v[188:191], v[220:223], v[68:71]
	v_mfma_f32_16x16x32_bf16 v[120:123], v[184:187], v[200:203], v[120:123]
	v_mfma_f32_16x16x32_bf16 v[116:119], v[192:195], v[200:203], v[116:119]
	v_mfma_f32_16x16x32_bf16 v[104:107], v[184:187], v[208:211], v[104:107]
	v_mfma_f32_16x16x32_bf16 v[100:103], v[192:195], v[208:211], v[100:103]
	v_mfma_f32_16x16x32_bf16 v[88:91], v[184:187], v[216:219], v[88:91]
	v_mfma_f32_16x16x32_bf16 v[84:87], v[192:195], v[216:219], v[84:87]
	v_mfma_f32_16x16x32_bf16 v[72:75], v[184:187], v[224:227], v[72:75]
	v_mfma_f32_16x16x32_bf16 v[68:71], v[192:195], v[224:227], v[68:71]
	s_barrier
	s_add_i32 s55, s55, s24
	v_lshl_add_u64 v[144:145], s[40:41], 0, v[174:175]
	s_mov_b32 m0, s55
	ds_read_b128 v[196:199], v155 offset:16384
	ds_read_b128 v[200:203], v155 offset:17408
	ds_read_b128 v[204:207], v155 offset:18432
	ds_read_b128 v[208:211], v155 offset:19456
	ds_read_b128 v[212:215], v155 offset:20480
	ds_read_b128 v[216:219], v155 offset:21504
	ds_read_b128 v[220:223], v155 offset:22528
	ds_read_b128 v[224:227], v155 offset:23552
	global_load_lds_dwordx4 v[144:145], off
	s_add_i32 m0, s55, 0x2000
	s_add_u32 s56, s40, 0x80000
	v_lshl_add_u64 v[228:229], s[40:41], 0, v[132:133]
	s_addc_u32 s57, s41, 0
	s_add_i32 s55, s58, s24
	global_load_lds_dwordx4 v[228:229], off
	v_lshl_add_u64 v[230:231], s[56:57], 0, v[174:175]
	s_mov_b32 m0, s55
	v_lshl_add_u64 v[232:233], s[26:27], 0, v[134:135]
	global_load_lds_dwordx4 v[230:231], off
	v_lshl_add_u64 v[230:231], s[56:57], 0, v[132:133]
	s_add_i32 m0, s55, 0x2000
	s_nop 0
	global_load_lds_dwordx4 v[230:231], off
	v_lshl_add_u64 v[230:231], s[26:27], 0, v[136:137]
	s_mov_b32 m0, s25
	s_nop 0
	global_load_lds_dwordx4 v[230:231], off
	s_mov_b32 m0, s42
	s_nop 0
	global_load_lds_dwordx4 v[232:233], off
	s_waitcnt vmcnt(24)
	s_waitcnt lgkmcnt(0)
	s_barrier
	s_waitcnt lgkmcnt(0)
	v_mfma_f32_16x16x32_bf16 v[64:67], v[148:151], v[196:199], v[64:67]
	v_mfma_f32_16x16x32_bf16 v[60:63], v[160:163], v[196:199], v[60:63]
	v_mfma_f32_16x16x32_bf16 v[52:55], v[148:151], v[204:207], v[52:55]
	v_mfma_f32_16x16x32_bf16 v[44:47], v[160:163], v[204:207], v[44:47]
	v_mfma_f32_16x16x32_bf16 v[36:39], v[148:151], v[212:215], v[36:39]
	v_mfma_f32_16x16x32_bf16 v[28:31], v[160:163], v[212:215], v[28:31]
	v_mfma_f32_16x16x32_bf16 v[20:23], v[148:151], v[220:223], v[20:23]
	v_mfma_f32_16x16x32_bf16 v[12:15], v[160:163], v[220:223], v[12:15]
	v_mfma_f32_16x16x32_bf16 v[64:67], v[156:159], v[200:203], v[64:67]
	v_mfma_f32_16x16x32_bf16 v[60:63], v[164:167], v[200:203], v[60:63]
	v_mfma_f32_16x16x32_bf16 v[52:55], v[156:159], v[208:211], v[52:55]
	v_mfma_f32_16x16x32_bf16 v[44:47], v[164:167], v[208:211], v[44:47]
	v_mfma_f32_16x16x32_bf16 v[36:39], v[156:159], v[216:219], v[36:39]
	v_mfma_f32_16x16x32_bf16 v[28:31], v[164:167], v[216:219], v[28:31]
	v_mfma_f32_16x16x32_bf16 v[20:23], v[156:159], v[224:227], v[20:23]
	v_mfma_f32_16x16x32_bf16 v[12:15], v[164:167], v[224:227], v[12:15]
	v_mfma_f32_16x16x32_bf16 v[56:59], v[168:171], v[196:199], v[56:59]
	v_mfma_f32_16x16x32_bf16 v[48:51], v[188:191], v[196:199], v[48:51]
	v_mfma_f32_16x16x32_bf16 v[40:43], v[168:171], v[204:207], v[40:43]
	v_mfma_f32_16x16x32_bf16 v[32:35], v[188:191], v[204:207], v[32:35]
	v_mfma_f32_16x16x32_bf16 v[24:27], v[168:171], v[212:215], v[24:27]
	v_mfma_f32_16x16x32_bf16 v[16:19], v[188:191], v[212:215], v[16:19]
	v_mfma_f32_16x16x32_bf16 v[8:11], v[168:171], v[220:223], v[8:11]
	v_mfma_f32_16x16x32_bf16 v[4:7], v[188:191], v[220:223], v[4:7]
	v_mfma_f32_16x16x32_bf16 v[56:59], v[184:187], v[200:203], v[56:59]
	v_mfma_f32_16x16x32_bf16 v[48:51], v[192:195], v[200:203], v[48:51]
	v_mfma_f32_16x16x32_bf16 v[40:43], v[184:187], v[208:211], v[40:43]
	v_mfma_f32_16x16x32_bf16 v[32:35], v[192:195], v[208:211], v[32:35]
	v_mfma_f32_16x16x32_bf16 v[24:27], v[184:187], v[216:219], v[24:27]
	v_mfma_f32_16x16x32_bf16 v[16:19], v[192:195], v[216:219], v[16:19]
	v_mfma_f32_16x16x32_bf16 v[8:11], v[184:187], v[224:227], v[8:11]
	v_mfma_f32_16x16x32_bf16 v[4:7], v[192:195], v[224:227], v[4:7]
	s_barrier
; #define PG8_STAGE(bufoff, gbase, voff) do { _Pragma("unroll") for (int _i = 0; _i < 2; ++_i) \
;         __builtin_amdgcn_global_load_lds((const unsigned*)((const char*)(gbase) + (voff)[_i]), (PG8_LAS unsigned*)(lds + (bufoff) + ldsw + _i * 8192), 16, 0, 0); } while (0)
; #define PG8_LDA(dst, b, h) do { _Pragma("unroll") for (int m = 0; m < 4; ++m) _Pragma("unroll") for (int k = 0; k < 2; ++k) dst[m][k] = *(const PG8_LAS bf16x8*)(lds + PG8_SA(b, h) + aoff + m * 2048 + k * 1024); } while (0)
; #define PG8_LDB(dst, b, h) do { _Pragma("unroll") for (int n = 0; n < 2; ++n) _Pragma("unroll") for (int k = 0; k < 2; ++k) dst[n][k] = *(const PG8_LAS bf16x8*)(lds + PG8_SB(b, h) + boff + n * 2048 + k * 1024); } while (0)
; #define PG8_MMA(ai, bj, At, Bt) do { __builtin_amdgcn_s_setprio(1); _Pragma("unroll") for (int m = 0; m < 4; ++m) _Pragma("unroll") for (int n = 0; n < 2; ++n) _Pragma("unroll") for (int k = 0; k < 2; ++k) \
;         acc[ai][bj][m][n] = __builtin_amdgcn_mfma_f32_16x16x32_bf16(Bt[n][k], At[m][k], acc[ai][bj][m][n], 0, 0, 0); __builtin_amdgcn_s_setprio(0); } while (0)
; #define PG8_WAIT_V(n) asm volatile("s_waitcnt vmcnt(" #n ")" ::: "memory")
; #define PG8_WAIT_L(n) asm volatile("s_waitcnt lgkmcnt(" #n ")" ::: "memory")
; #define PG8_BAR __builtin_amdgcn_s_barrier()
; #define PG8_SCHED __builtin_amdgcn_sched_barrier(0)
; template <class Epi, class Sched, bool ALIGN_EPI = false, bool SP2 = false>
; __device__ __forceinline__ void gemm_phase(PG8_LAS unsigned char* lds, const Gemm g, const Sched& S, const Epi& E) {
;     ...
;             PG8_LDB(B0, 1, 0); PG8_LDB(B1, 1, 1); PG8_SCHED; PG8_LDA(At, 1, 0); PG8_STAGE(PG8_SA(0, 1), a2 + hstep, voffA);
;             PG8_WAIT_V(8); PG8_WAIT_L(0); PG8_BAR; PG8_MMA(0, 0, At, B0); PG8_MMA(0, 1, At, B1); PG8_BAR; PG8_SCHED;
	s_add_i32 s55, 0, 0x18000
	v_add_u32_e32 v142, s55, v147
	s_add_i32 s56, 0, 0x1c000
	ds_read_b128 v[148:151], v142
	ds_read_b128 v[156:159], v142 offset:1024
	ds_read_b128 v[160:163], v142 offset:2048
	ds_read_b128 v[164:167], v142 offset:3072
	v_add_u32_e32 v142, s56, v147
	ds_read_b128 v[168:171], v142
	ds_read_b128 v[184:187], v142 offset:1024
	ds_read_b128 v[188:191], v142 offset:2048
	ds_read_b128 v[192:195], v142 offset:3072
	s_add_u32 s26, s26, 0x80000
	s_addc_u32 s27, s27, 0
	s_mov_b32 m0, s43
	v_lshl_add_u64 v[234:235], s[26:27], 0, v[136:137]
	ds_read_b128 v[196:199], v155 offset:32768
	ds_read_b128 v[200:203], v155 offset:33792
	ds_read_b128 v[204:207], v155 offset:34816
	ds_read_b128 v[208:211], v155 offset:35840
	ds_read_b128 v[212:215], v155 offset:36864
	ds_read_b128 v[216:219], v155 offset:37888
	ds_read_b128 v[220:223], v155 offset:38912
	ds_read_b128 v[224:227], v155 offset:39936
	global_load_lds_dwordx4 v[234:235], off
	v_lshl_add_u64 v[234:235], s[26:27], 0, v[134:135]
	s_mov_b32 m0, s44
	s_nop 0
	global_load_lds_dwordx4 v[234:235], off
	s_waitcnt vmcnt(8)
	s_waitcnt lgkmcnt(0)
	s_barrier
	s_waitcnt lgkmcnt(0)
	v_mfma_f32_16x16x32_bf16 v[128:131], v[148:151], v[196:199], v[128:131]
	v_mfma_f32_16x16x32_bf16 v[124:127], v[160:163], v[196:199], v[124:127]
	v_mfma_f32_16x16x32_bf16 v[112:115], v[148:151], v[204:207], v[112:115]
	v_mfma_f32_16x16x32_bf16 v[108:111], v[160:163], v[204:207], v[108:111]
	v_mfma_f32_16x16x32_bf16 v[96:99], v[148:151], v[212:215], v[96:99]
	v_mfma_f32_16x16x32_bf16 v[92:95], v[160:163], v[212:215], v[92:95]
	v_mfma_f32_16x16x32_bf16 v[80:83], v[148:151], v[220:223], v[80:83]
	v_mfma_f32_16x16x32_bf16 v[76:79], v[160:163], v[220:223], v[76:79]
	v_mfma_f32_16x16x32_bf16 v[128:131], v[156:159], v[200:203], v[128:131]
	v_mfma_f32_16x16x32_bf16 v[124:127], v[164:167], v[200:203], v[124:127]
	v_mfma_f32_16x16x32_bf16 v[112:115], v[156:159], v[208:211], v[112:115]
	v_mfma_f32_16x16x32_bf16 v[108:111], v[164:167], v[208:211], v[108:111]
	v_mfma_f32_16x16x32_bf16 v[96:99], v[156:159], v[216:219], v[96:99]
	v_mfma_f32_16x16x32_bf16 v[92:95], v[164:167], v[216:219], v[92:95]
	v_mfma_f32_16x16x32_bf16 v[80:83], v[156:159], v[224:227], v[80:83]
	v_mfma_f32_16x16x32_bf16 v[76:79], v[164:167], v[224:227], v[76:79]
	v_mfma_f32_16x16x32_bf16 v[120:123], v[168:171], v[196:199], v[120:123]
	v_mfma_f32_16x16x32_bf16 v[116:119], v[188:191], v[196:199], v[116:119]
	v_mfma_f32_16x16x32_bf16 v[104:107], v[168:171], v[204:207], v[104:107]
	v_mfma_f32_16x16x32_bf16 v[100:103], v[188:191], v[204:207], v[100:103]
	v_mfma_f32_16x16x32_bf16 v[88:91], v[168:171], v[212:215], v[88:91]
	v_mfma_f32_16x16x32_bf16 v[84:87], v[188:191], v[212:215], v[84:87]
	v_mfma_f32_16x16x32_bf16 v[72:75], v[168:171], v[220:223], v[72:75]
	v_mfma_f32_16x16x32_bf16 v[68:71], v[188:191], v[220:223], v[68:71]
	v_mfma_f32_16x16x32_bf16 v[120:123], v[184:187], v[200:203], v[120:123]
	v_mfma_f32_16x16x32_bf16 v[116:119], v[192:195], v[200:203], v[116:119]
	v_mfma_f32_16x16x32_bf16 v[104:107], v[184:187], v[208:211], v[104:107]
	v_mfma_f32_16x16x32_bf16 v[100:103], v[192:195], v[208:211], v[100:103]
	v_mfma_f32_16x16x32_bf16 v[88:91], v[184:187], v[216:219], v[88:91]
	v_mfma_f32_16x16x32_bf16 v[84:87], v[192:195], v[216:219], v[84:87]
	v_mfma_f32_16x16x32_bf16 v[72:75], v[184:187], v[224:227], v[72:75]
	v_mfma_f32_16x16x32_bf16 v[68:71], v[192:195], v[224:227], v[68:71]
	s_barrier
; #define PG8_STAGE(bufoff, gbase, voff) do { _Pragma("unroll") for (int _i = 0; _i < 2; ++_i) \
;         __builtin_amdgcn_global_load_lds((const unsigned*)((const char*)(gbase) + (voff)[_i]), (PG8_LAS unsigned*)(lds + (bufoff) + ldsw + _i * 8192), 16, 0, 0); } while (0)
; #define PG8_LDA(dst, b, h) do { _Pragma("unroll") for (int m = 0; m < 4; ++m) _Pragma("unroll") for (int k = 0; k < 2; ++k) dst[m][k] = *(const PG8_LAS bf16x8*)(lds + PG8_SA(b, h) + aoff + m * 2048 + k * 1024); } while (0)
; #define PG8_MMA(ai, bj, At, Bt) do { __builtin_amdgcn_s_setprio(1); _Pragma("unroll") for (int m = 0; m < 4; ++m) _Pragma("unroll") for (int n = 0; n < 2; ++n) _Pragma("unroll") for (int k = 0; k < 2; ++k) \
;         acc[ai][bj][m][n] = __builtin_amdgcn_mfma_f32_16x16x32_bf16(Bt[n][k], At[m][k], acc[ai][bj][m][n], 0, 0, 0); __builtin_amdgcn_s_setprio(0); } while (0)
; #define PG8_WAIT_V(n) asm volatile("s_waitcnt vmcnt(" #n ")" ::: "memory")
; #define PG8_WAIT_L(n) asm volatile("s_waitcnt lgkmcnt(" #n ")" ::: "memory")
; #define PG8_BAR __builtin_amdgcn_s_barrier()
; #define PG8_SCHED __builtin_amdgcn_sched_barrier(0)
; template <class Epi, class Sched, bool ALIGN_EPI = false, bool SP2 = false>
; __device__ __forceinline__ void gemm_phase(PG8_LAS unsigned char* lds, const Gemm g, const Sched& S, const Epi& E) {
;     ...
;         for (int t = 0; t < nt; t += 2) {
;             const bool last = (t == nt - 2);
;             const char* a1 = cA + (size_t)(t + 1) * kstep;
;             const char* a2 = last ? nA : cA + (size_t)(t + 2) * kstep; const char* b2 = last ? nB : cB + (size_t)(t + 2) * kstep;
;     ...
;             PG8_LDA(At, 1, 1); PG8_STAGE(PG8_SB(1, 0), b3, voffB); PG8_STAGE(PG8_SB(1, 1), b3 + hstep, voffB); PG8_STAGE(PG8_SA(1, 0), a3, voffA);
;             PG8_WAIT_V(8); PG8_WAIT_L(0); PG8_BAR; PG8_MMA(1, 0, At, B0); PG8_MMA(1, 1, At, B1); PG8_BAR; PG8_SCHED;
	s_add_i32 s26, s55, s24
	v_lshl_add_u64 v[144:145], v[144:145], 0, s[10:11]
	s_mov_b32 m0, s26
	ds_read_b128 v[196:199], v155 offset:49152
	ds_read_b128 v[200:203], v155 offset:50176
	ds_read_b128 v[204:207], v155 offset:51200
	ds_read_b128 v[208:211], v155 offset:52224
	ds_read_b128 v[212:215], v155 offset:53248
	ds_read_b128 v[216:219], v155 offset:54272
	ds_read_b128 v[220:223], v155 offset:55296
	ds_read_b128 v[224:227], v155 offset:56320
	global_load_lds_dwordx4 v[144:145], off
	s_add_i32 m0, s26, 0x2000
	s_add_u32 s26, s40, 0x80080
	v_lshl_add_u64 v[144:145], v[228:229], 0, s[10:11]
	s_addc_u32 s27, s41, 0
	s_add_i32 s40, s56, s24
	global_load_lds_dwordx4 v[144:145], off
	v_lshl_add_u64 v[144:145], s[26:27], 0, v[174:175]
	s_mov_b32 m0, s40
	s_nop 0
	global_load_lds_dwordx4 v[144:145], off
	v_lshl_add_u64 v[144:145], s[26:27], 0, v[132:133]
	s_add_i32 m0, s40, 0x2000
	s_nop 0
	global_load_lds_dwordx4 v[144:145], off
	v_lshl_add_u64 v[144:145], v[230:231], 0, s[10:11]
	s_mov_b32 m0, s20
	s_nop 0
	global_load_lds_dwordx4 v[144:145], off
	v_lshl_add_u64 v[144:145], v[232:233], 0, s[10:11]
	s_mov_b32 m0, s45
	s_nop 0
	global_load_lds_dwordx4 v[144:145], off
	s_waitcnt vmcnt(8)
	s_waitcnt lgkmcnt(0)
	s_barrier
	s_waitcnt lgkmcnt(0)
	v_mfma_f32_16x16x32_bf16 v[64:67], v[148:151], v[196:199], v[64:67]
	v_mfma_f32_16x16x32_bf16 v[60:63], v[160:163], v[196:199], v[60:63]
	v_mfma_f32_16x16x32_bf16 v[52:55], v[148:151], v[204:207], v[52:55]
	v_mfma_f32_16x16x32_bf16 v[44:47], v[160:163], v[204:207], v[44:47]
	v_mfma_f32_16x16x32_bf16 v[36:39], v[148:151], v[212:215], v[36:39]
	v_mfma_f32_16x16x32_bf16 v[28:31], v[160:163], v[212:215], v[28:31]
	v_mfma_f32_16x16x32_bf16 v[20:23], v[148:151], v[220:223], v[20:23]
	v_mfma_f32_16x16x32_bf16 v[12:15], v[160:163], v[220:223], v[12:15]
	v_mfma_f32_16x16x32_bf16 v[64:67], v[156:159], v[200:203], v[64:67]
	v_mfma_f32_16x16x32_bf16 v[60:63], v[164:167], v[200:203], v[60:63]
	v_mfma_f32_16x16x32_bf16 v[52:55], v[156:159], v[208:211], v[52:55]
	v_mfma_f32_16x16x32_bf16 v[44:47], v[164:167], v[208:211], v[44:47]
	v_mfma_f32_16x16x32_bf16 v[36:39], v[156:159], v[216:219], v[36:39]
	v_mfma_f32_16x16x32_bf16 v[28:31], v[164:167], v[216:219], v[28:31]
	v_mfma_f32_16x16x32_bf16 v[20:23], v[156:159], v[224:227], v[20:23]
	v_mfma_f32_16x16x32_bf16 v[12:15], v[164:167], v[224:227], v[12:15]
	v_mfma_f32_16x16x32_bf16 v[56:59], v[168:171], v[196:199], v[56:59]
	v_mfma_f32_16x16x32_bf16 v[48:51], v[188:191], v[196:199], v[48:51]
	v_mfma_f32_16x16x32_bf16 v[40:43], v[168:171], v[204:207], v[40:43]
	v_mfma_f32_16x16x32_bf16 v[32:35], v[188:191], v[204:207], v[32:35]
	v_mfma_f32_16x16x32_bf16 v[24:27], v[168:171], v[212:215], v[24:27]
	v_mfma_f32_16x16x32_bf16 v[16:19], v[188:191], v[212:215], v[16:19]
	v_mfma_f32_16x16x32_bf16 v[8:11], v[168:171], v[220:223], v[8:11]
	v_mfma_f32_16x16x32_bf16 v[4:7], v[188:191], v[220:223], v[4:7]
	v_mfma_f32_16x16x32_bf16 v[56:59], v[184:187], v[200:203], v[56:59]
	v_mfma_f32_16x16x32_bf16 v[48:51], v[192:195], v[200:203], v[48:51]
	v_mfma_f32_16x16x32_bf16 v[40:43], v[184:187], v[208:211], v[40:43]
	v_mfma_f32_16x16x32_bf16 v[32:35], v[192:195], v[208:211], v[32:35]
	v_mfma_f32_16x16x32_bf16 v[24:27], v[184:187], v[216:219], v[24:27]
	v_mfma_f32_16x16x32_bf16 v[16:19], v[192:195], v[216:219], v[16:19]
	v_mfma_f32_16x16x32_bf16 v[8:11], v[184:187], v[224:227], v[8:11]
	v_mfma_f32_16x16x32_bf16 v[4:7], v[192:195], v[224:227], v[4:7]
	s_barrier
	s_add_i32 s54, s54, 2
	s_add_u32 s52, s52, 0x100
	s_addc_u32 s53, s53, 0
	s_add_u32 s38, s38, 0x100
	s_addc_u32 s39, s39, 0
	s_cmp_gt_u32 s54, 29
	s_branch .LBB0_86

; template <class Epi, class Sched, bool ALIGN_EPI = false, bool SP2 = false>
; __device__ __forceinline__ void gemm_phase(PG8_LAS unsigned char* lds, const Gemm g, const Sched& S, const Epi& E) {
;     ...
;         const bool has_next = S.next(ui + 1, nxt);
;         const char* nA = has_next ? (const char*)g.A + (size_t)nxt.pm * tstep : cA; const char* nB = has_next ? (const char*)g.Bt + (size_t)nxt.pn * tstep : cB;
;     ...
; #pragma unroll
;         for (int a = 0; a < 2; ++a)
; #pragma unroll
;             for (int b = 0; b < 2; ++b)
; #pragma unroll
;                 for (int m = 0; m < 4; ++m)
; #pragma unroll
;                     for (int n = 0; n < 2; ++n) acc[a][b][m][n] = (f32x4){0.f, 0.f, 0.f, 0.f};
;         cur = nxt; cA = nA; cB = nB; ++ui;
.LBB0_406:
	s_ashr_i32 s51, s50, 31
	s_lshl_b64 s[16:17], s[50:51], 20
	s_add_u32 s52, s19, s16
	s_addc_u32 s53, s20, s17
	s_and_b64 s[16:17], s[40:41], exec
	s_cselect_b32 s23, s53, s15
	s_cselect_b32 s24, s52, s14
	s_ashr_i32 s49, s48, 31
	s_lshl_b64 s[16:17], s[48:49], 20
	s_add_u32 s54, s26, s16
	s_addc_u32 s55, s27, s17
	s_and_b64 s[16:17], s[40:41], exec
	s_cselect_b32 s25, s55, s1
	s_cselect_b32 s49, s54, s0
	s_add_u32 s51, s0, 0x100
	s_addc_u32 s57, s1, 0
	s_add_u32 s0, s14, 0x80080
	v_mov_b32_e32 v4, 0
	s_addc_u32 s1, s15, 0
	s_mov_b32 s58, -2
	v_mov_b32_e32 v5, v4
	v_mov_b32_e32 v6, v4
	v_mov_b32_e32 v7, v4
	v_mov_b32_e32 v8, v4
	v_mov_b32_e32 v9, v4
	v_mov_b32_e32 v10, v4
	v_mov_b32_e32 v11, v4
	v_mov_b32_e32 v12, v4
	v_mov_b32_e32 v13, v4
	v_mov_b32_e32 v14, v4
	v_mov_b32_e32 v15, v4
	v_mov_b32_e32 v16, v4
	v_mov_b32_e32 v17, v4
	v_mov_b32_e32 v18, v4
	v_mov_b32_e32 v19, v4
	v_mov_b32_e32 v20, v4
	v_mov_b32_e32 v21, v4
	v_mov_b32_e32 v22, v4
	v_mov_b32_e32 v23, v4
	v_mov_b32_e32 v24, v4
	v_mov_b32_e32 v25, v4
	v_mov_b32_e32 v26, v4
	v_mov_b32_e32 v27, v4
	s_waitcnt vmcnt(0)
	v_mov_b32_e32 v28, v4
	v_mov_b32_e32 v29, v4
	v_mov_b32_e32 v30, v4
	v_mov_b32_e32 v31, v4
	v_mov_b32_e32 v32, v4
	v_mov_b32_e32 v33, v4
	v_mov_b32_e32 v34, v4
	v_mov_b32_e32 v35, v4
	v_mov_b32_e32 v68, v4
	v_mov_b32_e32 v69, v4
	v_mov_b32_e32 v70, v4
	v_mov_b32_e32 v71, v4
	v_mov_b32_e32 v72, v4
	v_mov_b32_e32 v73, v4
	v_mov_b32_e32 v74, v4
	v_mov_b32_e32 v75, v4
	v_mov_b32_e32 v76, v4
	v_mov_b32_e32 v77, v4
	v_mov_b32_e32 v78, v4
	v_mov_b32_e32 v79, v4
	v_mov_b32_e32 v80, v4
	v_mov_b32_e32 v81, v4
	v_mov_b32_e32 v82, v4
	v_mov_b32_e32 v83, v4
	v_mov_b32_e32 v84, v4
	v_mov_b32_e32 v85, v4
	v_mov_b32_e32 v86, v4
	v_mov_b32_e32 v87, v4
	v_mov_b32_e32 v88, v4
	v_mov_b32_e32 v89, v4
	v_mov_b32_e32 v90, v4
	v_mov_b32_e32 v91, v4
	v_mov_b32_e32 v92, v4
	v_mov_b32_e32 v93, v4
	v_mov_b32_e32 v94, v4
	v_mov_b32_e32 v95, v4
	v_mov_b32_e32 v96, v4
	v_mov_b32_e32 v97, v4
	v_mov_b32_e32 v98, v4
	v_mov_b32_e32 v99, v4
	v_mov_b32_e32 v36, v4
	v_mov_b32_e32 v37, v4
	v_mov_b32_e32 v38, v4
	v_mov_b32_e32 v39, v4
	v_mov_b32_e32 v40, v4
	v_mov_b32_e32 v41, v4
	v_mov_b32_e32 v42, v4
	v_mov_b32_e32 v43, v4
	v_mov_b32_e32 v44, v4
	v_mov_b32_e32 v45, v4
	v_mov_b32_e32 v46, v4
	v_mov_b32_e32 v47, v4
	v_mov_b32_e32 v48, v4
	v_mov_b32_e32 v49, v4
	v_mov_b32_e32 v50, v4
	v_mov_b32_e32 v51, v4
	v_mov_b32_e32 v52, v4
	v_mov_b32_e32 v53, v4
	v_mov_b32_e32 v54, v4
	v_mov_b32_e32 v55, v4
	v_mov_b32_e32 v56, v4
	v_mov_b32_e32 v57, v4
	v_mov_b32_e32 v58, v4
	v_mov_b32_e32 v59, v4
	v_mov_b32_e32 v60, v4
	v_mov_b32_e32 v61, v4
	v_mov_b32_e32 v62, v4
	v_mov_b32_e32 v63, v4
	v_mov_b32_e32 v64, v4
	v_mov_b32_e32 v65, v4
	v_mov_b32_e32 v66, v4
	v_mov_b32_e32 v67, v4
	v_mov_b32_e32 v108, v4
	v_mov_b32_e32 v109, v4
	v_mov_b32_e32 v110, v4
	v_mov_b32_e32 v111, v4
	v_mov_b32_e32 v112, v4
	v_mov_b32_e32 v113, v4
	v_mov_b32_e32 v114, v4
	v_mov_b32_e32 v115, v4
	v_mov_b32_e32 v116, v4
	v_mov_b32_e32 v117, v4
	v_mov_b32_e32 v118, v4
	v_mov_b32_e32 v119, v4
	v_mov_b32_e32 v120, v4
	v_mov_b32_e32 v121, v4
	v_mov_b32_e32 v122, v4
	v_mov_b32_e32 v123, v4
	v_mov_b32_e32 v124, v4
	v_mov_b32_e32 v125, v4
	v_mov_b32_e32 v126, v4
	v_mov_b32_e32 v127, v4
	v_mov_b32_e32 v128, v4
	v_mov_b32_e32 v129, v4
	v_mov_b32_e32 v130, v4
	v_mov_b32_e32 v131, v4
	v_mov_b32_e32 v132, v4
	v_mov_b32_e32 v133, v4
	v_mov_b32_e32 v134, v4
	v_mov_b32_e32 v135, v4
	v_mov_b32_e32 v136, v4
	v_mov_b32_e32 v137, v4
	v_mov_b32_e32 v138, v4
	v_mov_b32_e32 v139, v4
	s_setprio 0

; template <class Epi, class Sched, bool ALIGN_EPI = false, bool SP2 = false>
; __device__ __forceinline__ void gemm_phase(PG8_LAS unsigned char* lds, const Gemm g, const Sched& S, const Epi& E) {
;     ...
;         const bool has_next = S.next(ui + 1, nxt);
;         const char* nA = has_next ? (const char*)g.A + (size_t)nxt.pm * tstep : cA; const char* nB = has_next ? (const char*)g.Bt + (size_t)nxt.pn * tstep : cB;
;     ...
; #pragma unroll
;         for (int a = 0; a < 2; ++a)
; #pragma unroll
;             for (int b = 0; b < 2; ++b)
; #pragma unroll
;                 for (int m = 0; m < 4; ++m)
; #pragma unroll
;                     for (int n = 0; n < 2; ++n) acc[a][b][m][n] = (f32x4){0.f, 0.f, 0.f, 0.f};
;         cur = nxt; cA = nA; cB = nB; ++ui;
.LBB0_484:
	s_ashr_i32 s53, s52, 31
	s_lshl_b64 s[16:17], s[52:53], 21
	s_add_u32 s54, s19, s16
	s_addc_u32 s55, s20, s17
	s_and_b64 s[16:17], s[40:41], exec
	s_cselect_b32 s23, s55, s15
	s_cselect_b32 s24, s54, s14
	s_ashr_i32 s51, s50, 31
	s_lshl_b64 s[16:17], s[50:51], 21
	s_add_u32 s56, s26, s16
	s_addc_u32 s57, s27, s17
	s_and_b64 s[16:17], s[40:41], exec
	s_cselect_b32 s25, s57, s1
	s_cselect_b32 s51, s56, s0
	s_add_u32 s53, s0, 0x100
	s_addc_u32 s59, s1, 0
	s_add_u32 s0, s14, 0x100080
	v_mov_b32_e32 v4, 0
	s_addc_u32 s1, s15, 0
	s_mov_b32 s60, -2
	v_mov_b32_e32 v5, v4
	v_mov_b32_e32 v6, v4
	v_mov_b32_e32 v7, v4
	v_mov_b32_e32 v8, v4
	v_mov_b32_e32 v9, v4
	v_mov_b32_e32 v10, v4
	v_mov_b32_e32 v11, v4
	v_mov_b32_e32 v12, v4
	v_mov_b32_e32 v13, v4
	v_mov_b32_e32 v14, v4
	v_mov_b32_e32 v15, v4
	v_mov_b32_e32 v16, v4
	v_mov_b32_e32 v17, v4
	v_mov_b32_e32 v18, v4
	v_mov_b32_e32 v19, v4
	v_mov_b32_e32 v20, v4
	v_mov_b32_e32 v21, v4
	v_mov_b32_e32 v22, v4
	v_mov_b32_e32 v23, v4
	v_mov_b32_e32 v24, v4
	v_mov_b32_e32 v25, v4
	v_mov_b32_e32 v26, v4
	v_mov_b32_e32 v27, v4
	s_waitcnt vmcnt(0)
	v_mov_b32_e32 v28, v4
	v_mov_b32_e32 v29, v4
	v_mov_b32_e32 v30, v4
	v_mov_b32_e32 v31, v4
	v_mov_b32_e32 v32, v4
	v_mov_b32_e32 v33, v4
	v_mov_b32_e32 v34, v4
	v_mov_b32_e32 v35, v4
	v_mov_b32_e32 v68, v4
	v_mov_b32_e32 v69, v4
	v_mov_b32_e32 v70, v4
	v_mov_b32_e32 v71, v4
	v_mov_b32_e32 v72, v4
	v_mov_b32_e32 v73, v4
	v_mov_b32_e32 v74, v4
	v_mov_b32_e32 v75, v4
	v_mov_b32_e32 v76, v4
	v_mov_b32_e32 v77, v4
	v_mov_b32_e32 v78, v4
	v_mov_b32_e32 v79, v4
	v_mov_b32_e32 v80, v4
	v_mov_b32_e32 v81, v4
	v_mov_b32_e32 v82, v4
	v_mov_b32_e32 v83, v4
	v_mov_b32_e32 v84, v4
	v_mov_b32_e32 v85, v4
	v_mov_b32_e32 v86, v4
	v_mov_b32_e32 v87, v4
	v_mov_b32_e32 v88, v4
	v_mov_b32_e32 v89, v4
	v_mov_b32_e32 v90, v4
	v_mov_b32_e32 v91, v4
	v_mov_b32_e32 v92, v4
	v_mov_b32_e32 v93, v4
	v_mov_b32_e32 v94, v4
	v_mov_b32_e32 v95, v4
	v_mov_b32_e32 v96, v4
	v_mov_b32_e32 v97, v4
	v_mov_b32_e32 v98, v4
	v_mov_b32_e32 v99, v4
	v_mov_b32_e32 v36, v4
	v_mov_b32_e32 v37, v4
	v_mov_b32_e32 v38, v4
	v_mov_b32_e32 v39, v4
	v_mov_b32_e32 v40, v4
	v_mov_b32_e32 v41, v4
	v_mov_b32_e32 v42, v4
	v_mov_b32_e32 v43, v4
	v_mov_b32_e32 v44, v4
	v_mov_b32_e32 v45, v4
	v_mov_b32_e32 v46, v4
	v_mov_b32_e32 v47, v4
	v_mov_b32_e32 v48, v4
	v_mov_b32_e32 v49, v4
	v_mov_b32_e32 v50, v4
	v_mov_b32_e32 v51, v4
	v_mov_b32_e32 v52, v4
	v_mov_b32_e32 v53, v4
	v_mov_b32_e32 v54, v4
	v_mov_b32_e32 v55, v4
	v_mov_b32_e32 v56, v4
	v_mov_b32_e32 v57, v4
	v_mov_b32_e32 v58, v4
	v_mov_b32_e32 v59, v4
	v_mov_b32_e32 v60, v4
	v_mov_b32_e32 v61, v4
	v_mov_b32_e32 v62, v4
	v_mov_b32_e32 v63, v4
	v_mov_b32_e32 v64, v4
	v_mov_b32_e32 v65, v4
	v_mov_b32_e32 v66, v4
	v_mov_b32_e32 v67, v4
	v_mov_b32_e32 v108, v4
	v_mov_b32_e32 v109, v4
	v_mov_b32_e32 v110, v4
	v_mov_b32_e32 v111, v4
	v_mov_b32_e32 v112, v4
	v_mov_b32_e32 v113, v4
	v_mov_b32_e32 v114, v4
	v_mov_b32_e32 v115, v4
	v_mov_b32_e32 v116, v4
	v_mov_b32_e32 v117, v4
	v_mov_b32_e32 v118, v4
	v_mov_b32_e32 v119, v4
	v_mov_b32_e32 v120, v4
	v_mov_b32_e32 v121, v4
	v_mov_b32_e32 v122, v4
	v_mov_b32_e32 v123, v4
	v_mov_b32_e32 v124, v4
	v_mov_b32_e32 v125, v4
	v_mov_b32_e32 v126, v4
	v_mov_b32_e32 v127, v4
	v_mov_b32_e32 v128, v4
	v_mov_b32_e32 v129, v4
	v_mov_b32_e32 v130, v4
	v_mov_b32_e32 v131, v4
	v_mov_b32_e32 v132, v4
	v_mov_b32_e32 v133, v4
	v_mov_b32_e32 v134, v4
	v_mov_b32_e32 v135, v4
	v_mov_b32_e32 v136, v4
	v_mov_b32_e32 v137, v4
	v_mov_b32_e32 v138, v4
	v_mov_b32_e32 v139, v4
	s_setprio 0

; template <class Epi, class Sched, bool ALIGN_EPI = false, bool SP2 = false>
; __device__ __forceinline__ void gemm_phase(PG8_LAS unsigned char* lds, const Gemm g, const Sched& S, const Epi& E) {
;     ...
;         const bool has_next = S.next(ui + 1, nxt);
;         const char* nA = has_next ? (const char*)g.A + (size_t)nxt.pm * tstep : cA; const char* nB = has_next ? (const char*)g.Bt + (size_t)nxt.pn * tstep : cB;
;     ...
; #pragma unroll
;         for (int a = 0; a < 2; ++a)
; #pragma unroll
;             for (int b = 0; b < 2; ++b)
; #pragma unroll
;                 for (int m = 0; m < 4; ++m)
; #pragma unroll
;                     for (int n = 0; n < 2; ++n) acc[a][b][m][n] = (f32x4){0.f, 0.f, 0.f, 0.f};
;         cur = nxt; cA = nA; cB = nB; ++ui;
.LBB0_562:
	s_ashr_i32 s39, s38, 31
	s_lshl_b64 s[26:27], s[38:39], 20
	s_add_u32 s44, s22, s26
	s_addc_u32 s45, s23, s27
	s_and_b64 s[26:27], s[42:43], exec
	s_cselect_b32 s39, s45, s19
	s_cselect_b32 s59, s44, s18
	s_ashr_i32 s37, s36, 31
	s_lshl_b64 s[26:27], s[36:37], 20
	s_add_u32 s46, s24, s26
	s_addc_u32 s47, s25, s27
	s_and_b64 s[26:27], s[42:43], exec
	s_cselect_b32 s37, s47, s1
	s_cselect_b32 s60, s46, s0
	s_add_u32 s61, s0, 0x100
	s_addc_u32 s62, s1, 0
	s_add_u32 s0, s18, 0x80080
	v_mov_b32_e32 v4, 0
	s_addc_u32 s1, s19, 0
	s_mov_b32 s63, -2
	s_waitcnt lgkmcnt(0)
	v_mov_b32_e32 v5, v4
	v_mov_b32_e32 v6, v4
	v_mov_b32_e32 v7, v4
	v_mov_b32_e32 v8, v4
	v_mov_b32_e32 v9, v4
	v_mov_b32_e32 v10, v4
	v_mov_b32_e32 v11, v4
	v_mov_b32_e32 v20, v4
	v_mov_b32_e32 v21, v4
	v_mov_b32_e32 v22, v4
	v_mov_b32_e32 v23, v4
	v_mov_b32_e32 v24, v4
	v_mov_b32_e32 v25, v4
	v_mov_b32_e32 v26, v4
	v_mov_b32_e32 v27, v4
	s_waitcnt vmcnt(0)
	v_mov_b32_e32 v36, v4
	v_mov_b32_e32 v37, v4
	v_mov_b32_e32 v38, v4
	v_mov_b32_e32 v39, v4
	v_mov_b32_e32 v40, v4
	v_mov_b32_e32 v41, v4
	v_mov_b32_e32 v42, v4
	v_mov_b32_e32 v43, v4
	v_mov_b32_e32 v52, v4
	v_mov_b32_e32 v53, v4
	v_mov_b32_e32 v54, v4
	v_mov_b32_e32 v55, v4
	v_mov_b32_e32 v56, v4
	v_mov_b32_e32 v57, v4
	v_mov_b32_e32 v58, v4
	v_mov_b32_e32 v59, v4
	v_mov_b32_e32 v12, v4
	v_mov_b32_e32 v13, v4
	v_mov_b32_e32 v14, v4
	v_mov_b32_e32 v15, v4
	v_mov_b32_e32 v16, v4
	v_mov_b32_e32 v17, v4
	v_mov_b32_e32 v18, v4
	v_mov_b32_e32 v19, v4
	v_mov_b32_e32 v28, v4
	v_mov_b32_e32 v29, v4
	v_mov_b32_e32 v30, v4
	v_mov_b32_e32 v31, v4
	v_mov_b32_e32 v32, v4
	v_mov_b32_e32 v33, v4
	v_mov_b32_e32 v34, v4
	v_mov_b32_e32 v35, v4
	v_mov_b32_e32 v44, v4
	v_mov_b32_e32 v45, v4
	v_mov_b32_e32 v46, v4
	v_mov_b32_e32 v47, v4
	v_mov_b32_e32 v48, v4
	v_mov_b32_e32 v49, v4
	v_mov_b32_e32 v50, v4
	v_mov_b32_e32 v51, v4
	v_mov_b32_e32 v60, v4
	v_mov_b32_e32 v61, v4
	v_mov_b32_e32 v62, v4
	v_mov_b32_e32 v63, v4
	v_mov_b32_e32 v64, v4
	v_mov_b32_e32 v65, v4
	v_mov_b32_e32 v66, v4
	v_mov_b32_e32 v67, v4
	v_mov_b32_e32 v68, v4
	v_mov_b32_e32 v69, v4
	v_mov_b32_e32 v70, v4
	v_mov_b32_e32 v71, v4
	v_mov_b32_e32 v72, v4
	v_mov_b32_e32 v73, v4
	v_mov_b32_e32 v74, v4
	v_mov_b32_e32 v75, v4
	v_mov_b32_e32 v84, v4
	v_mov_b32_e32 v85, v4
	v_mov_b32_e32 v86, v4
	v_mov_b32_e32 v87, v4
	v_mov_b32_e32 v88, v4
	v_mov_b32_e32 v89, v4
	v_mov_b32_e32 v90, v4
	v_mov_b32_e32 v91, v4
	v_mov_b32_e32 v100, v4
	v_mov_b32_e32 v101, v4
	v_mov_b32_e32 v102, v4
	v_mov_b32_e32 v103, v4
	v_mov_b32_e32 v104, v4
	v_mov_b32_e32 v105, v4
	v_mov_b32_e32 v106, v4
	v_mov_b32_e32 v107, v4
	v_mov_b32_e32 v116, v4
	v_mov_b32_e32 v117, v4
	v_mov_b32_e32 v118, v4
	v_mov_b32_e32 v119, v4
	v_mov_b32_e32 v120, v4
	v_mov_b32_e32 v121, v4
	v_mov_b32_e32 v122, v4
	v_mov_b32_e32 v123, v4
	v_mov_b32_e32 v76, v4
	v_mov_b32_e32 v77, v4
	v_mov_b32_e32 v78, v4
	v_mov_b32_e32 v79, v4
	v_mov_b32_e32 v80, v4
	v_mov_b32_e32 v81, v4
	v_mov_b32_e32 v82, v4
	v_mov_b32_e32 v83, v4
	v_mov_b32_e32 v92, v4
	v_mov_b32_e32 v93, v4
	v_mov_b32_e32 v94, v4
	v_mov_b32_e32 v95, v4
	v_mov_b32_e32 v96, v4
	v_mov_b32_e32 v97, v4
	v_mov_b32_e32 v98, v4
	v_mov_b32_e32 v99, v4
	v_mov_b32_e32 v108, v4
	v_mov_b32_e32 v109, v4
	v_mov_b32_e32 v110, v4
	v_mov_b32_e32 v111, v4
	v_mov_b32_e32 v112, v4
	v_mov_b32_e32 v113, v4
	v_mov_b32_e32 v114, v4
	v_mov_b32_e32 v115, v4
	v_mov_b32_e32 v124, v4
	v_mov_b32_e32 v125, v4
	v_mov_b32_e32 v126, v4
	v_mov_b32_e32 v127, v4
	v_mov_b32_e32 v128, v4
	v_mov_b32_e32 v129, v4
	v_mov_b32_e32 v130, v4
	v_mov_b32_e32 v131, v4
	s_setprio 0

; template <class Epi, class Sched, bool ALIGN_EPI = false, bool SP2 = false>
; __device__ __forceinline__ void gemm_phase(PG8_LAS unsigned char* lds, const Gemm g, const Sched& S, const Epi& E) {
;     ...
;         const bool has_next = S.next(ui + 1, nxt);
;         const char* nA = has_next ? (const char*)g.A + (size_t)nxt.pm * tstep : cA; const char* nB = has_next ? (const char*)g.Bt + (size_t)nxt.pn * tstep : cB;
;     ...
; #pragma unroll
;         for (int a = 0; a < 2; ++a)
; #pragma unroll
;             for (int b = 0; b < 2; ++b)
; #pragma unroll
;                 for (int m = 0; m < 4; ++m)
; #pragma unroll
;                     for (int n = 0; n < 2; ++n) acc[a][b][m][n] = (f32x4){0.f, 0.f, 0.f, 0.f};
;         cur = nxt; cA = nA; cB = nB; ++ui;
.LBB0_659:
	s_ashr_i32 s65, s64, 31
	s_lshl_b64 s[16:17], s[64:65], 20
	s_add_u32 s66, s19, s16
	s_addc_u32 s67, s20, s17
	s_and_b64 s[16:17], s[40:41], exec
	s_cselect_b32 s23, s67, s15
	s_cselect_b32 s24, s66, s14
	s_ashr_i32 s63, s62, 31
	s_lshl_b64 s[16:17], s[62:63], 20
	s_add_u32 s68, s26, s16
	s_addc_u32 s69, s27, s17
	s_and_b64 s[16:17], s[40:41], exec
	s_cselect_b32 s25, s69, s1
	s_cselect_b32 s42, s68, s0
	s_add_u32 s43, s0, 0x100
	s_addc_u32 s44, s1, 0
	s_add_u32 s0, s14, 0x80080
	v_mov_b32_e32 v4, 0
	s_addc_u32 s1, s15, 0
	s_mov_b32 s45, -2
	v_mov_b32_e32 v5, v4
	v_mov_b32_e32 v6, v4
	v_mov_b32_e32 v7, v4
	v_mov_b32_e32 v8, v4
	v_mov_b32_e32 v9, v4
	v_mov_b32_e32 v10, v4
	v_mov_b32_e32 v11, v4
	v_mov_b32_e32 v12, v4
	v_mov_b32_e32 v13, v4
	v_mov_b32_e32 v14, v4
	v_mov_b32_e32 v15, v4
	v_mov_b32_e32 v16, v4
	v_mov_b32_e32 v17, v4
	v_mov_b32_e32 v18, v4
	v_mov_b32_e32 v19, v4
	v_mov_b32_e32 v20, v4
	v_mov_b32_e32 v21, v4
	v_mov_b32_e32 v22, v4
	v_mov_b32_e32 v23, v4
	v_mov_b32_e32 v24, v4
	v_mov_b32_e32 v25, v4
	v_mov_b32_e32 v26, v4
	v_mov_b32_e32 v27, v4
	s_waitcnt vmcnt(0)
	v_mov_b32_e32 v28, v4
	v_mov_b32_e32 v29, v4
	v_mov_b32_e32 v30, v4
	v_mov_b32_e32 v31, v4
	v_mov_b32_e32 v32, v4
	v_mov_b32_e32 v33, v4
	v_mov_b32_e32 v34, v4
	v_mov_b32_e32 v35, v4
	v_mov_b32_e32 v88, v4
	v_mov_b32_e32 v89, v4
	v_mov_b32_e32 v90, v4
	v_mov_b32_e32 v91, v4
	v_mov_b32_e32 v92, v4
	v_mov_b32_e32 v93, v4
	v_mov_b32_e32 v94, v4
	v_mov_b32_e32 v95, v4
	v_mov_b32_e32 v52, v4
	v_mov_b32_e32 v53, v4
	v_mov_b32_e32 v54, v4
	v_mov_b32_e32 v55, v4
	v_mov_b32_e32 v56, v4
	v_mov_b32_e32 v57, v4
	v_mov_b32_e32 v58, v4
	v_mov_b32_e32 v59, v4
	v_mov_b32_e32 v60, v4
	v_mov_b32_e32 v61, v4
	v_mov_b32_e32 v62, v4
	v_mov_b32_e32 v63, v4
	v_mov_b32_e32 v64, v4
	v_mov_b32_e32 v65, v4
	v_mov_b32_e32 v66, v4
	v_mov_b32_e32 v67, v4
	v_mov_b32_e32 v68, v4
	v_mov_b32_e32 v69, v4
	v_mov_b32_e32 v70, v4
	v_mov_b32_e32 v71, v4
	v_mov_b32_e32 v72, v4
	v_mov_b32_e32 v73, v4
	v_mov_b32_e32 v74, v4
	v_mov_b32_e32 v75, v4
	v_mov_b32_e32 v100, v4
	v_mov_b32_e32 v101, v4
	v_mov_b32_e32 v102, v4
	v_mov_b32_e32 v103, v4
	v_mov_b32_e32 v104, v4
	v_mov_b32_e32 v105, v4
	v_mov_b32_e32 v106, v4
	v_mov_b32_e32 v107, v4
	v_mov_b32_e32 v108, v4
	v_mov_b32_e32 v109, v4
	v_mov_b32_e32 v110, v4
	v_mov_b32_e32 v111, v4
	v_mov_b32_e32 v112, v4
	v_mov_b32_e32 v113, v4
	v_mov_b32_e32 v114, v4
	v_mov_b32_e32 v115, v4
	v_mov_b32_e32 v116, v4
	v_mov_b32_e32 v117, v4
	v_mov_b32_e32 v118, v4
	v_mov_b32_e32 v119, v4
	v_mov_b32_e32 v120, v4
	v_mov_b32_e32 v121, v4
	v_mov_b32_e32 v122, v4
	v_mov_b32_e32 v123, v4
	v_mov_b32_e32 v140, v4
	v_mov_b32_e32 v141, v4
	v_mov_b32_e32 v142, v4
	v_mov_b32_e32 v143, v4
	v_mov_b32_e32 v144, v4
	v_mov_b32_e32 v145, v4
	v_mov_b32_e32 v146, v4
	v_mov_b32_e32 v147, v4
	v_mov_b32_e32 v156, v4
	v_mov_b32_e32 v157, v4
	v_mov_b32_e32 v158, v4
	v_mov_b32_e32 v159, v4
	v_mov_b32_e32 v160, v4
	v_mov_b32_e32 v161, v4
	v_mov_b32_e32 v162, v4
	v_mov_b32_e32 v163, v4
	v_mov_b32_e32 v124, v4
	v_mov_b32_e32 v125, v4
	v_mov_b32_e32 v126, v4
	v_mov_b32_e32 v127, v4
	v_mov_b32_e32 v128, v4
	v_mov_b32_e32 v129, v4
	v_mov_b32_e32 v130, v4
	v_mov_b32_e32 v131, v4
	v_mov_b32_e32 v132, v4
	v_mov_b32_e32 v133, v4
	v_mov_b32_e32 v134, v4
	v_mov_b32_e32 v135, v4
	v_mov_b32_e32 v136, v4
	v_mov_b32_e32 v137, v4
	v_mov_b32_e32 v138, v4
	v_mov_b32_e32 v139, v4
	v_mov_b32_e32 v148, v4
	v_mov_b32_e32 v149, v4
	v_mov_b32_e32 v150, v4
	v_mov_b32_e32 v151, v4
	v_mov_b32_e32 v152, v4
	v_mov_b32_e32 v153, v4
	v_mov_b32_e32 v154, v4
	v_mov_b32_e32 v155, v4
	s_setprio 0

; template <class Epi, class Sched, bool ALIGN_EPI = false, bool SP2 = false>
; __device__ __forceinline__ void gemm_phase(PG8_LAS unsigned char* lds, const Gemm g, const Sched& S, const Epi& E) {
;     ...
;         const bool has_next = S.next(ui + 1, nxt);
;         const char* nA = has_next ? (const char*)g.A + (size_t)nxt.pm * tstep : cA; const char* nB = has_next ? (const char*)g.Bt + (size_t)nxt.pn * tstep : cB;
;     ...
; #pragma unroll
;         for (int a = 0; a < 2; ++a)
; #pragma unroll
;             for (int b = 0; b < 2; ++b)
; #pragma unroll
;                 for (int m = 0; m < 4; ++m)
; #pragma unroll
;                     for (int n = 0; n < 2; ++n) acc[a][b][m][n] = (f32x4){0.f, 0.f, 0.f, 0.f};
;         cur = nxt; cA = nA; cB = nB; ++ui;
.LBB0_821:
	s_add_u32 s23, s14, 0x100
	v_mov_b32_e32 v4, 0
	s_addc_u32 s24, s15, 0
	s_mov_b32 s25, -2
	s_waitcnt lgkmcnt(0)
	v_mov_b32_e32 v5, v4
	v_mov_b32_e32 v6, v4
	v_mov_b32_e32 v7, v4
	v_mov_b32_e32 v8, v4
	v_mov_b32_e32 v9, v4
	v_mov_b32_e32 v10, v4
	v_mov_b32_e32 v11, v4
	v_mov_b32_e32 v20, v4
	v_mov_b32_e32 v21, v4
	v_mov_b32_e32 v22, v4
	v_mov_b32_e32 v23, v4
	v_mov_b32_e32 v24, v4
	v_mov_b32_e32 v25, v4
	v_mov_b32_e32 v26, v4
	v_mov_b32_e32 v27, v4
	s_waitcnt vmcnt(0)
	v_mov_b32_e32 v36, v4
	v_mov_b32_e32 v37, v4
	v_mov_b32_e32 v38, v4
	v_mov_b32_e32 v39, v4
	v_mov_b32_e32 v40, v4
	v_mov_b32_e32 v41, v4
	v_mov_b32_e32 v42, v4
	v_mov_b32_e32 v43, v4
	v_mov_b32_e32 v52, v4
	v_mov_b32_e32 v53, v4
	v_mov_b32_e32 v54, v4
	v_mov_b32_e32 v55, v4
	v_mov_b32_e32 v56, v4
	v_mov_b32_e32 v57, v4
	v_mov_b32_e32 v58, v4
	v_mov_b32_e32 v59, v4
	v_mov_b32_e32 v12, v4
	v_mov_b32_e32 v13, v4
	v_mov_b32_e32 v14, v4
	v_mov_b32_e32 v15, v4
	v_mov_b32_e32 v16, v4
	v_mov_b32_e32 v17, v4
	v_mov_b32_e32 v18, v4
	v_mov_b32_e32 v19, v4
	v_mov_b32_e32 v28, v4
	v_mov_b32_e32 v29, v4
	v_mov_b32_e32 v30, v4
	v_mov_b32_e32 v31, v4
	v_mov_b32_e32 v32, v4
	v_mov_b32_e32 v33, v4
	v_mov_b32_e32 v34, v4
	v_mov_b32_e32 v35, v4
	v_mov_b32_e32 v44, v4
	v_mov_b32_e32 v45, v4
	v_mov_b32_e32 v46, v4
	v_mov_b32_e32 v47, v4
	v_mov_b32_e32 v48, v4
	v_mov_b32_e32 v49, v4
	v_mov_b32_e32 v50, v4
	v_mov_b32_e32 v51, v4
	v_mov_b32_e32 v60, v4
	v_mov_b32_e32 v61, v4
	v_mov_b32_e32 v62, v4
	v_mov_b32_e32 v63, v4
	v_mov_b32_e32 v64, v4
	v_mov_b32_e32 v65, v4
	v_mov_b32_e32 v66, v4
	v_mov_b32_e32 v67, v4
	v_mov_b32_e32 v68, v4
	v_mov_b32_e32 v69, v4
	v_mov_b32_e32 v70, v4
	v_mov_b32_e32 v71, v4
	v_mov_b32_e32 v72, v4
	v_mov_b32_e32 v73, v4
	v_mov_b32_e32 v74, v4
	v_mov_b32_e32 v75, v4
	v_mov_b32_e32 v84, v4
	v_mov_b32_e32 v85, v4
	v_mov_b32_e32 v86, v4
	v_mov_b32_e32 v87, v4
	v_mov_b32_e32 v88, v4
	v_mov_b32_e32 v89, v4
	v_mov_b32_e32 v90, v4
	v_mov_b32_e32 v91, v4
	v_mov_b32_e32 v100, v4
	v_mov_b32_e32 v101, v4
	v_mov_b32_e32 v102, v4
	v_mov_b32_e32 v103, v4
	v_mov_b32_e32 v104, v4
	v_mov_b32_e32 v105, v4
	v_mov_b32_e32 v106, v4
	v_mov_b32_e32 v107, v4
	v_mov_b32_e32 v124, v4
	v_mov_b32_e32 v125, v4
	v_mov_b32_e32 v126, v4
	v_mov_b32_e32 v127, v4
	v_mov_b32_e32 v128, v4
	v_mov_b32_e32 v129, v4
	v_mov_b32_e32 v130, v4
	v_mov_b32_e32 v131, v4
	v_mov_b32_e32 v76, v4
	v_mov_b32_e32 v77, v4
	v_mov_b32_e32 v78, v4
	v_mov_b32_e32 v79, v4
	v_mov_b32_e32 v80, v4
	v_mov_b32_e32 v81, v4
	v_mov_b32_e32 v82, v4
	v_mov_b32_e32 v83, v4
	v_mov_b32_e32 v92, v4
	v_mov_b32_e32 v93, v4
	v_mov_b32_e32 v94, v4
	v_mov_b32_e32 v95, v4
	v_mov_b32_e32 v96, v4
	v_mov_b32_e32 v97, v4
	v_mov_b32_e32 v98, v4
	v_mov_b32_e32 v99, v4
	v_mov_b32_e32 v108, v4
	v_mov_b32_e32 v109, v4
	v_mov_b32_e32 v110, v4
	v_mov_b32_e32 v111, v4
	v_mov_b32_e32 v112, v4
	v_mov_b32_e32 v113, v4
	v_mov_b32_e32 v114, v4
	v_mov_b32_e32 v115, v4
	v_mov_b32_e32 v132, v4
	v_mov_b32_e32 v133, v4
	v_mov_b32_e32 v134, v4
	v_mov_b32_e32 v135, v4
	v_mov_b32_e32 v136, v4
	v_mov_b32_e32 v137, v4
	v_mov_b32_e32 v138, v4
	v_mov_b32_e32 v139, v4
	s_setprio 0
